# grid barriers: returning arrival atomic, last arriver bumps 8 per-group release words, waiters poll release words instead of the arrival counter; phase-1 tile map rebalanced; beta/g epilogue a_log/dt_
# speedup vs baseline: 1.1497x; 1.1081x over previous
; __device__ __forceinline__ void grid_barrier(unsigned* ctr, const unsigned k) {
;   __syncthreads();
;   if (threadIdx.x == 0) {
;     __hip_atomic_fetch_add(ctr, 1u, __ATOMIC_RELEASE, __HIP_MEMORY_SCOPE_AGENT);
;     const unsigned target = k * gridDim.x;
;     while (__hip_atomic_load(ctr, __ATOMIC_RELAXED, __HIP_MEMORY_SCOPE_AGENT) < target) __builtin_amdgcn_s_sleep(1);
;     __builtin_amdgcn_fence(__ATOMIC_ACQUIRE, "agent");
;   }
;   __syncthreads();
; }
.LBB0_73:
	s_waitcnt vmcnt(0) lgkmcnt(0)
	s_barrier
	v_cmp_eq_u32_e32 vcc, 0, v218
	s_and_saveexec_b64 s[4:5], vcc
	s_cbranch_execz .LBB0_83
	s_add_u32 s6, s50, 0xf223cb0
	s_addc_u32 s7, s51, 0
	buffer_wbl2 sc1
	s_waitcnt vmcnt(0)
	v_mov_b32_e32 v0, 0
	v_mov_b32_e32 v1, 1
	global_atomic_add v1, v0, v1, s[6:7] sc0
	s_waitcnt vmcnt(0)
	v_readfirstlane_b32 s8, v1
	s_nop 3
	s_add_i32 s8, s8, 1
	s_cmp_eq_u32 s8, s3
	s_cbranch_scc0 .Lgbar1_poll
	v_mov_b32_e32 v1, 1
	global_atomic_add v0, v1, s[6:7] offset:80
	global_atomic_add v0, v1, s[6:7] offset:144
	global_atomic_add v0, v1, s[6:7] offset:208
	global_atomic_add v0, v1, s[6:7] offset:272
	global_atomic_add v0, v1, s[6:7] offset:336
	global_atomic_add v0, v1, s[6:7] offset:400
	global_atomic_add v0, v1, s[6:7] offset:464
	global_atomic_add v0, v1, s[6:7] offset:528
	s_branch .Lgbar1_done
.Lgbar1_poll:
	s_and_b32 s8, s89, 7
	s_lshl_b32 s8, s8, 6
	v_mov_b32_e32 v0, s8
.Lgbar1_loop:
	global_load_dword v1, v0, s[6:7] offset:80 sc1
	s_waitcnt vmcnt(0)
	v_cmp_le_u32_e32 vcc, 1, v1
	s_cbranch_vccnz .Lgbar1_done
	s_sleep 2
	s_branch .Lgbar1_loop

; __device__ __forceinline__ void phase1(const Params& p, unsigned char* smem) {
;     ...
;   const int xcd = blockIdx.x & 7, lw = blockIdx.x >> 3, LW = (gridDim.x - xcd + 7) >> 3;
;   for (int i = lw;; i += LW) {
;     int mt, nt; if (!tile_map(i, xcd, 129, 49, mt, nt)) break;
;     const int m0 = mt * 128;
;     const int n0 = nt < 24 ? nt * 128 : (nt < 48 ? 4096 + (nt - 24) * 128 : 8192);
;     ...
;             else { float z = v[h] + p.dt_bias[h]; float sp = z > 20.f ? z : log1pf(__expf(z)); GG[o] = -__expf(p.a_log[h]) * sp; }
.LBB0_83:
	s_or_b64 exec, exec, s[4:5]
	s_add_u32 s12, s48, 0x2010000
	s_addc_u32 s13, s49, 0
	s_add_u32 s14, s50, 0x2010000
	s_addc_u32 s15, s51, 0
	s_add_u32 s16, s50, 0x4050000
	s_addc_u32 s17, s51, 0
	s_add_u32 s18, s50, 0x6090000
	s_addc_u32 s19, s51, 0
	s_and_b32 s73, s89, 7
	s_xor_b32 s2, s73, 7
	s_add_i32 s2, s3, s2
	s_lshr_b32 s65, s2, 3
	s_sub_i32 s2, 0x88, s73
	s_lshr_b32 s33, s89, 3
	s_lshr_b32 s2, s2, 3
	s_add_u32 s20, s48, 0x80
	s_addc_u32 s21, s49, 0
	s_add_u32 s22, s48, 0x10080
	s_load_dwordx4 s[8:11], s[0:1], 0x50
	s_addc_u32 s23, s49, 0
	s_add_u32 s24, s48, 0x20080
	s_addc_u32 s25, s49, 0
	s_add_u32 s26, s48, 0x30080
	s_addc_u32 s27, s49, 0
	v_mov_b32_e32 v97, 0
	s_mov_b32 s37, 0x10000
	s_mov_b32 s44, 0x20000
	s_mov_b32 s45, 0x30000
	s_movk_i32 s46, 0x90
	s_mov_b32 s47, 0xfffffc0
	s_mov_b64 s[28:29], 0x3fff
	s_mov_b64 s[30:31], 0x3fdf
	s_mov_b64 s[34:35], 0x3fbf
	s_movk_i32 s52, 0x210
	s_movk_i32 s53, 0x2010
	s_movk_i32 s54, 0x2008
	s_movk_i32 s55, 0x4020
	s_mov_b32 s56, 0x7fc01ff1
	s_mov_b32 s57, 0x41a00000
	s_mov_b32 s58, 0x3f2aaaab
	v_mov_b32_e32 v110, 0x3ecc95a3
	s_mov_b32 s59, 0x3f317218
	s_mov_b32 s60, 0x7f800000
	s_mov_b32 s61, 0x33800000
	s_movk_i32 s62, 0xdff0
	s_movk_i32 s63, 0x81
	s_movk_i32 s64, 0x300
	s_movk_i32 s66, 0x4080
	s_mov_b32 s36, 0x3e38aa3b
	v_mov_b32_e32 v111, 0x3fff
	v_mov_b32_e32 v112, 0x3fdf
	v_mov_b32_e32 v113, 0x3fbf
	v_mov_b32_e32 v98, 0x3f317218
	v_mov_b32_e32 v114, 0x7f800000
	v_mov_b32_e32 v115, 0x7fc00000
	v_mov_b32_e32 v116, 0xff800000
	s_mov_b32 s67, s33
	s_barrier
	s_waitcnt lgkmcnt(0)
	s_load_dwordx8 s[76:83], s[10:11], 0x0
	s_load_dwordx8 s[92:99], s[8:9], 0x0
	s_waitcnt lgkmcnt(0)
	s_branch .LBB0_87

; __device__ __forceinline__ bool tile_map(int i, int xcd, int MT, int NT, int& mt, int& nt) {
;   int cm = (MT - xcd + 7) >> 3;
;   int ag = i / (8 * NT);
;   if (ag * 8 >= cm) return false;
;   int gs = cm - ag * 8; if (gs > 8) gs = 8;
;   int j = i - ag * 8 * NT;
;   if (j >= gs * NT) return false;
;   int al = j % gs; nt = j / gs;
;   mt = xcd + 8 * (8 * ag + al);
;   return true;
; }
; __device__ __forceinline__ void phase1(const Params& p, unsigned char* smem) {
;     ...
;     int mt, nt; if (!tile_map(i, xcd, 129, 49, mt, nt)) break;
;     const int m0 = mt * 128;
;     const int n0 = nt < 24 ? nt * 128 : (nt < 48 ? 4096 + (nt - 24) * 128 : 8192);
.LBB0_87:
	s_mov_b64 s[4:5], 0
	s_cmpk_ge_u32 s67, 0x310
	s_cbranch_scc1 .Ltm1_extra
	s_cmpk_ge_u32 s67, 0x188
	s_cselect_b32 s6, 0x188, 0
	s_cselect_b32 s7, 64, 0
	s_sub_i32 s38, s67, s6
	s_lshr_b32 s68, s38, 3
	s_and_b32 s38, s38, 7
	s_lshl_b32 s38, s38, 3
	s_add_i32 s38, s38, s7
	s_or_b32 s69, s38, s73
	s_branch .Ltm1_swap
.Ltm1_extra:
	s_sub_i32 s38, s67, 0x320
	s_cmp_lt_i32 s38, 0
	s_cbranch_scc1 .LBB0_90
	s_lshl_b32 s38, s38, 3
	s_add_i32 s68, s38, s73
	s_cmp_gt_u32 s68, 48
	s_cbranch_scc1 .LBB0_90
	s_movk_i32 s69, 0x80
.Ltm1_swap:
	s_cmp_eq_u32 s68, 2
	s_cselect_b32 s38, 48, s68
	s_cmp_eq_u32 s68, 48
	s_cselect_b32 s68, 2, s38
	s_mov_b64 s[4:5], -1

; __device__ __forceinline__ void phase1(const Params& p, unsigned char* smem) {
;     ...
;             else { float z = v[h] + p.dt_bias[h]; float sp = z > 20.f ? z : log1pf(__expf(z)); GG[o] = -__expf(p.a_log[h]) * sp; }
.LBB0_106:
	s_or_b64 exec, exec, s[42:43]
	v_mov_b32_e32 v65, s99
	s_nop 0
	v_mul_f32_e32 v65, 0x3fb8aa3b, v65
	v_exp_f32_e32 v65, v65
	s_nop 0
	v_mul_f32_e64 v68, v64, -v65
	v_mov_b64_e32 v[64:65], 0xee9e000

; __device__ __forceinline__ void phase1(const Params& p, unsigned char* smem) {
;     ...
;             else { float z = v[h] + p.dt_bias[h]; float sp = z > 20.f ? z : log1pf(__expf(z)); GG[o] = -__expf(p.a_log[h]) * sp; }
.LBB0_112:
	s_or_saveexec_b64 s[40:41], s[40:41]
	v_mov_b64_e32 v[76:77], 0xee1d000
	s_xor_b64 exec, exec, s[40:41]
	s_cbranch_execz .LBB0_116
	v_mov_b32_e32 v75, s76
	s_waitcnt lgkmcnt(1)
	v_add_f32_e32 v68, v68, v75
	v_cmp_nlt_f32_e32 vcc, s57, v68
	s_and_saveexec_b64 s[42:43], vcc
	s_cbranch_execz .LBB0_115
	v_mul_f32_e32 v68, 0x3fb8aa3b, v68
	v_exp_f32_e32 v68, v68
	s_nop 0
	v_add_f32_e32 v75, 1.0, v68
	v_frexp_mant_f32_e32 v80, v75
	v_cvt_f64_f32_e32 v[76:77], v75
	v_add_f32_e32 v79, -1.0, v75
	v_frexp_exp_i32_f64_e32 v76, v[76:77]
	v_cmp_gt_f32_e32 vcc, s58, v80
	v_sub_f32_e32 v81, v79, v75
	v_sub_f32_e32 v79, v68, v79
	v_subbrev_co_u32_e32 v86, vcc, 0, v76, vcc
	v_add_f32_e32 v81, 1.0, v81
	v_sub_u32_e32 v76, 0, v86
	v_add_f32_e32 v79, v79, v81
	v_ldexp_f32 v75, v75, v76
	v_ldexp_f32 v76, v79, v76
	v_add_f32_e32 v79, -1.0, v75
	v_add_f32_e32 v77, 1.0, v79
	v_sub_f32_e32 v77, v75, v77
	v_add_f32_e32 v80, v76, v77
	v_add_f32_e32 v77, 1.0, v75
	v_add_f32_e32 v81, -1.0, v77
	v_sub_f32_e32 v75, v75, v81
	v_add_f32_e32 v75, v76, v75
	v_add_f32_e32 v87, v77, v75
	v_rcp_f32_e32 v88, v87
	v_sub_f32_e32 v76, v87, v77
	v_add_f32_e32 v77, v79, v80
	v_sub_f32_e32 v75, v75, v76
	v_sub_f32_e32 v76, v77, v79
	v_mul_f32_e32 v89, v77, v88
	v_sub_f32_e32 v79, v80, v76
	v_mul_f32_e32 v80, v87, v89
	v_fma_f32 v82, v89, v87, -v80
	v_fmac_f32_e32 v82, v89, v75
	v_add_f32_e32 v76, v80, v82
	v_sub_f32_e32 v81, v77, v76
	v_pk_add_f32 v[84:85], v[76:77], v[80:81] neg_lo:[0,1] neg_hi:[0,1]
	v_mov_b32_e32 v83, v76
	v_pk_add_f32 v[76:77], v[84:85], v[82:83] neg_lo:[0,1] neg_hi:[0,1]
	v_cmp_neq_f32_e32 vcc, s60, v68
	v_add_f32_e32 v77, v79, v77
	v_add_f32_e32 v76, v76, v77
	v_add_f32_e32 v77, v81, v76
	v_mul_f32_e32 v79, v88, v77
	v_mul_f32_e32 v80, v87, v79
	v_fma_f32 v82, v79, v87, -v80
	v_fmac_f32_e32 v82, v79, v75
	v_sub_f32_e32 v75, v81, v77
	v_add_f32_e32 v75, v76, v75
	v_add_f32_e32 v76, v80, v82
	v_sub_f32_e32 v81, v77, v76
	v_pk_add_f32 v[84:85], v[76:77], v[80:81] neg_lo:[0,1] neg_hi:[0,1]
	v_mov_b32_e32 v83, v76
	v_pk_add_f32 v[76:77], v[84:85], v[82:83] neg_lo:[0,1] neg_hi:[0,1]
	s_nop 0
	v_add_f32_e32 v75, v75, v77
	v_add_f32_e32 v75, v76, v75
	v_add_f32_e32 v77, v89, v79
	v_add_f32_e32 v75, v81, v75
	v_sub_f32_e32 v76, v77, v89
	v_mul_f32_e32 v75, v88, v75
	v_sub_f32_e32 v76, v79, v76
	v_add_f32_e32 v75, v76, v75
	v_add_f32_e32 v79, v77, v75
	v_mul_f32_e32 v80, v79, v79
	v_fmamk_f32 v76, v80, 0x3e9b6dac, v110
	v_fmaak_f32 v99, v80, v76, 0x3f2aaada
	v_cvt_f32_i32_e32 v76, v86
	v_sub_f32_e32 v77, v79, v77
	v_sub_f32_e32 v75, v75, v77
	v_mul_f32_e32 v77, v79, v80
	v_pk_mul_f32 v[82:83], v[76:77], v[98:99]
	v_ldexp_f32 v81, v79, 1
	v_fma_f32 v80, v76, s59, -v82
	v_fmac_f32_e32 v80, 0xb102e308, v76
	v_pk_add_f32 v[76:77], v[82:83], v[80:81]
	v_ldexp_f32 v75, v75, 1
	v_sub_f32_e32 v79, v77, v81
	v_sub_f32_e32 v79, v83, v79
	v_add_f32_e32 v85, v75, v79
	v_mov_b32_e32 v84, v82
	v_pk_add_f32 v[82:83], v[76:77], v[82:83] neg_lo:[0,1] neg_hi:[0,1]
	v_pk_add_f32 v[86:87], v[76:77], v[84:85]
	v_mov_b32_e32 v81, v76
	v_mov_b32_e32 v83, v87
	v_pk_add_f32 v[88:89], v[80:81], v[82:83] neg_lo:[0,1] neg_hi:[0,1]
	v_pk_add_f32 v[80:81], v[80:81], v[82:83]
	v_mov_b32_e32 v84, v85
	v_pk_add_f32 v[82:83], v[80:81], v[76:77] op_sel:[1,0] op_sel_hi:[0,1] neg_lo:[0,1] neg_hi:[0,1]
	v_pk_add_f32 v[90:91], v[86:87], v[82:83] op_sel_hi:[1,0] neg_lo:[0,1] neg_hi:[0,1]
	v_mov_b32_e32 v86, v87
	v_mov_b32_e32 v87, v81
	v_pk_mov_b32 v[82:83], v[76:77], v[82:83] op_sel:[1,0]
	v_mov_b32_e32 v85, v76
	v_pk_add_f32 v[82:83], v[86:87], v[82:83] neg_lo:[0,1] neg_hi:[0,1]
	v_mov_b32_e32 v90, v88
	v_pk_add_f32 v[76:77], v[84:85], v[82:83] neg_lo:[0,1] neg_hi:[0,1]
	v_mov_b32_e32 v89, v81
	v_pk_add_f32 v[82:83], v[90:91], v[76:77]
	s_nop 0
	v_pk_add_f32 v[84:85], v[82:83], v[82:83] op_sel:[0,1] op_sel_hi:[1,0]
	s_nop 0
	v_pk_add_f32 v[80:81], v[80:81], v[84:85] op_sel:[1,0] op_sel_hi:[0,1]
	v_mov_b32_e32 v83, v80
	v_pk_add_f32 v[86:87], v[82:83], v[88:89] neg_lo:[0,1] neg_hi:[0,1]
	v_mov_b32_e32 v77, v84
	v_sub_f32_e32 v75, v82, v86
	v_pk_add_f32 v[76:77], v[76:77], v[86:87] neg_lo:[0,1] neg_hi:[0,1]
	v_sub_f32_e32 v75, v88, v75
	v_add_f32_e32 v75, v76, v75
	v_add_f32_e32 v75, v75, v77
	v_add_f32_e32 v75, v80, v75
	v_cndmask_b32_e32 v75, v114, v75, vcc
	v_cmp_ngt_f32_e32 vcc, -1.0, v68
	s_nop 1
	v_cndmask_b32_e32 v75, v115, v75, vcc
	v_cmp_neq_f32_e32 vcc, -1.0, v68
	s_nop 1
	v_cndmask_b32_e32 v75, v116, v75, vcc
	v_cmp_lt_f32_e64 vcc, |v68|, s61
	s_nop 1
	v_cndmask_b32_e32 v68, v75, v68, vcc
.LBB0_115:
	s_or_b64 exec, exec, s[42:43]
	v_mov_b32_e32 v75, s92
	v_mov_b64_e32 v[76:77], 0xee9e000
	s_nop 0
	v_mul_f32_e32 v75, 0x3fb8aa3b, v75
	v_exp_f32_e32 v75, v75
	s_nop 0
	v_mul_f32_e64 v80, v68, -v75

; __device__ __forceinline__ void phase1(const Params& p, unsigned char* smem) {
;     ...
;             else { float z = v[h] + p.dt_bias[h]; float sp = z > 20.f ? z : log1pf(__expf(z)); GG[o] = -__expf(p.a_log[h]) * sp; }
.LBB0_118:
	s_or_saveexec_b64 s[40:41], s[40:41]
	v_mov_b64_e32 v[76:77], 0xee1d000
	s_xor_b64 exec, exec, s[40:41]
	s_cbranch_execz .LBB0_122
	v_mov_b32_e32 v68, s77
	s_nop 0
	v_add_f32_e32 v68, v69, v68
	v_cmp_nlt_f32_e32 vcc, s57, v68
	s_and_saveexec_b64 s[42:43], vcc
	s_cbranch_execz .LBB0_121
	v_mul_f32_e32 v68, 0x3fb8aa3b, v68
	v_exp_f32_e32 v90, v68
	s_nop 0
	v_add_f32_e32 v76, 1.0, v90
	v_frexp_mant_f32_e32 v80, v76
	v_cvt_f64_f32_e32 v[68:69], v76
	v_frexp_exp_i32_f64_e32 v68, v[68:69]
	v_cmp_gt_f32_e32 vcc, s58, v80
	v_add_f32_e32 v77, -1.0, v76
	v_sub_f32_e32 v81, v77, v76
	v_subbrev_co_u32_e32 v84, vcc, 0, v68, vcc
	v_sub_u32_e32 v68, 0, v84
	v_sub_f32_e32 v77, v90, v77
	v_add_f32_e32 v81, 1.0, v81
	v_ldexp_f32 v69, v76, v68
	v_add_f32_e32 v77, v77, v81
	v_add_f32_e32 v76, -1.0, v69
	v_add_f32_e32 v80, 1.0, v69
	v_ldexp_f32 v68, v77, v68
	v_add_f32_e32 v77, 1.0, v76
	v_add_f32_e32 v81, -1.0, v80
	v_sub_f32_e32 v77, v69, v77
	v_sub_f32_e32 v69, v69, v81
	v_add_f32_e32 v77, v68, v77
	v_add_f32_e32 v68, v68, v69
	v_add_f32_e32 v85, v80, v68
	v_rcp_f32_e32 v87, v85
	v_sub_f32_e32 v69, v85, v80
	v_sub_f32_e32 v86, v68, v69
	v_add_f32_e32 v69, v76, v77
	v_mul_f32_e32 v89, v69, v87
	v_sub_f32_e32 v68, v69, v76
	v_mul_f32_e32 v76, v85, v89
	v_fma_f32 v80, v89, v85, -v76
	v_fmac_f32_e32 v80, v89, v86
	v_sub_f32_e32 v88, v77, v68
	v_add_f32_e32 v68, v76, v80
	v_sub_f32_e32 v77, v69, v68
	v_pk_add_f32 v[82:83], v[68:69], v[76:77] neg_lo:[0,1] neg_hi:[0,1]
	v_mov_b32_e32 v81, v68
	v_pk_add_f32 v[68:69], v[82:83], v[80:81] neg_lo:[0,1] neg_hi:[0,1]
	v_cmp_neq_f32_e32 vcc, s60, v90
	v_add_f32_e32 v69, v88, v69
	v_add_f32_e32 v68, v68, v69
	v_add_f32_e32 v69, v77, v68
	v_mul_f32_e32 v88, v87, v69
	v_mul_f32_e32 v76, v85, v88
	v_fma_f32 v80, v88, v85, -v76
	v_fmac_f32_e32 v80, v88, v86
	v_sub_f32_e32 v77, v77, v69
	v_add_f32_e32 v85, v68, v77
	v_add_f32_e32 v68, v76, v80
	v_sub_f32_e32 v77, v69, v68
	v_pk_add_f32 v[82:83], v[68:69], v[76:77] neg_lo:[0,1] neg_hi:[0,1]
	v_mov_b32_e32 v81, v68
	v_pk_add_f32 v[68:69], v[82:83], v[80:81] neg_lo:[0,1] neg_hi:[0,1]
	s_nop 0
	v_add_f32_e32 v69, v85, v69
	v_add_f32_e32 v68, v68, v69
	v_add_f32_e32 v69, v89, v88
	v_add_f32_e32 v68, v77, v68
	v_sub_f32_e32 v76, v69, v89
	v_mul_f32_e32 v68, v87, v68
	v_sub_f32_e32 v76, v88, v76
	v_add_f32_e32 v76, v76, v68
	v_add_f32_e32 v80, v69, v76
	v_mul_f32_e32 v81, v80, v80
	v_fmamk_f32 v68, v81, 0x3e9b6dac, v110
	v_fmaak_f32 v99, v81, v68, 0x3f2aaada
	v_cvt_f32_i32_e32 v68, v84
	v_sub_f32_e32 v69, v80, v69
	v_sub_f32_e32 v69, v76, v69
	v_ldexp_f32 v82, v69, 1
	v_mul_f32_e32 v69, v80, v81
	v_ldexp_f32 v77, v80, 1
	v_pk_mul_f32 v[80:81], v[68:69], v[98:99]
	s_nop 0
	v_fma_f32 v76, v68, s59, -v80
	v_fmac_f32_e32 v76, 0xb102e308, v68
	v_pk_add_f32 v[68:69], v[80:81], v[76:77]
	s_nop 0
	v_sub_f32_e32 v77, v69, v77
	v_sub_f32_e32 v77, v81, v77
	v_add_f32_e32 v83, v82, v77
	v_mov_b32_e32 v82, v80
	v_pk_add_f32 v[80:81], v[68:69], v[80:81] neg_lo:[0,1] neg_hi:[0,1]
	v_pk_add_f32 v[84:85], v[68:69], v[82:83]
	v_mov_b32_e32 v77, v68
	v_mov_b32_e32 v81, v85
	v_pk_add_f32 v[86:87], v[76:77], v[80:81] neg_lo:[0,1] neg_hi:[0,1]
	v_pk_add_f32 v[76:77], v[76:77], v[80:81]
	v_mov_b32_e32 v82, v83
	v_pk_add_f32 v[80:81], v[76:77], v[68:69] op_sel:[1,0] op_sel_hi:[0,1] neg_lo:[0,1] neg_hi:[0,1]
	v_pk_add_f32 v[88:89], v[84:85], v[80:81] op_sel_hi:[1,0] neg_lo:[0,1] neg_hi:[0,1]
	v_mov_b32_e32 v84, v85
	v_mov_b32_e32 v85, v77
	v_pk_mov_b32 v[80:81], v[68:69], v[80:81] op_sel:[1,0]
	v_mov_b32_e32 v83, v68
	v_pk_add_f32 v[80:81], v[84:85], v[80:81] neg_lo:[0,1] neg_hi:[0,1]
	v_mov_b32_e32 v88, v86
	v_pk_add_f32 v[68:69], v[82:83], v[80:81] neg_lo:[0,1] neg_hi:[0,1]
	v_mov_b32_e32 v87, v77
	v_pk_add_f32 v[80:81], v[88:89], v[68:69]
	s_nop 0
	v_pk_add_f32 v[82:83], v[80:81], v[80:81] op_sel:[0,1] op_sel_hi:[1,0]
	s_nop 0
	v_pk_add_f32 v[76:77], v[76:77], v[82:83] op_sel:[1,0] op_sel_hi:[0,1]
	v_mov_b32_e32 v81, v76
	v_pk_add_f32 v[84:85], v[80:81], v[86:87] neg_lo:[0,1] neg_hi:[0,1]
	v_mov_b32_e32 v69, v82
	v_sub_f32_e32 v77, v80, v84
	v_pk_add_f32 v[68:69], v[68:69], v[84:85] neg_lo:[0,1] neg_hi:[0,1]
	v_sub_f32_e32 v77, v86, v77
	v_add_f32_e32 v68, v68, v77
	v_add_f32_e32 v68, v68, v69
	v_add_f32_e32 v68, v76, v68
	v_cndmask_b32_e32 v68, v114, v68, vcc
	v_cmp_ngt_f32_e32 vcc, -1.0, v90
	s_nop 1
	v_cndmask_b32_e32 v68, v115, v68, vcc
	v_cmp_neq_f32_e32 vcc, -1.0, v90
	s_nop 1
	v_cndmask_b32_e32 v68, v116, v68, vcc
	v_cmp_lt_f32_e64 vcc, |v90|, s61
	s_nop 1
	v_cndmask_b32_e32 v68, v68, v90, vcc
.LBB0_121:
	s_or_b64 exec, exec, s[42:43]
	v_mov_b32_e32 v69, s93
	v_mov_b64_e32 v[76:77], 0xee9e000
	s_nop 0
	v_mul_f32_e32 v69, 0x3fb8aa3b, v69
	v_exp_f32_e32 v69, v69
	s_nop 0
	v_mul_f32_e64 v68, v68, -v69

; __device__ __forceinline__ void phase1(const Params& p, unsigned char* smem) {
;     ...
;             else { float z = v[h] + p.dt_bias[h]; float sp = z > 20.f ? z : log1pf(__expf(z)); GG[o] = -__expf(p.a_log[h]) * sp; }
.LBB0_124:
	s_or_saveexec_b64 s[40:41], s[40:41]
	v_mov_b64_e32 v[68:69], 0xee1d000
	s_xor_b64 exec, exec, s[40:41]
	s_cbranch_execz .LBB0_128
	v_mov_b32_e32 v68, s78
	s_nop 0
	v_add_f32_e32 v68, v70, v68
	v_cmp_nlt_f32_e32 vcc, s57, v68
	s_and_saveexec_b64 s[42:43], vcc
	s_cbranch_execz .LBB0_127
	v_mul_f32_e32 v68, 0x3fb8aa3b, v68
	v_exp_f32_e32 v70, v68
	s_nop 0
	v_add_f32_e32 v76, 1.0, v70
	v_frexp_mant_f32_e32 v80, v76
	v_cvt_f64_f32_e32 v[68:69], v76
	v_frexp_exp_i32_f64_e32 v68, v[68:69]
	v_cmp_gt_f32_e32 vcc, s58, v80
	v_add_f32_e32 v77, -1.0, v76
	v_sub_f32_e32 v81, v77, v76
	v_subbrev_co_u32_e32 v84, vcc, 0, v68, vcc
	v_sub_u32_e32 v68, 0, v84
	v_sub_f32_e32 v77, v70, v77
	v_add_f32_e32 v81, 1.0, v81
	v_ldexp_f32 v69, v76, v68
	v_add_f32_e32 v77, v77, v81
	v_add_f32_e32 v76, -1.0, v69
	v_add_f32_e32 v80, 1.0, v69
	v_ldexp_f32 v68, v77, v68
	v_add_f32_e32 v77, 1.0, v76
	v_add_f32_e32 v81, -1.0, v80
	v_sub_f32_e32 v77, v69, v77
	v_sub_f32_e32 v69, v69, v81
	v_add_f32_e32 v77, v68, v77
	v_add_f32_e32 v68, v68, v69
	v_add_f32_e32 v85, v80, v68
	v_rcp_f32_e32 v87, v85
	v_sub_f32_e32 v69, v85, v80
	v_sub_f32_e32 v86, v68, v69
	v_add_f32_e32 v69, v76, v77
	v_mul_f32_e32 v89, v69, v87
	v_sub_f32_e32 v68, v69, v76
	v_mul_f32_e32 v76, v85, v89
	v_fma_f32 v80, v89, v85, -v76
	v_fmac_f32_e32 v80, v89, v86
	v_sub_f32_e32 v88, v77, v68
	v_add_f32_e32 v68, v76, v80
	v_sub_f32_e32 v77, v69, v68
	v_pk_add_f32 v[82:83], v[68:69], v[76:77] neg_lo:[0,1] neg_hi:[0,1]
	v_mov_b32_e32 v81, v68
	v_pk_add_f32 v[68:69], v[82:83], v[80:81] neg_lo:[0,1] neg_hi:[0,1]
	v_cmp_neq_f32_e32 vcc, s60, v70
	v_add_f32_e32 v69, v88, v69
	v_add_f32_e32 v68, v68, v69
	v_add_f32_e32 v69, v77, v68
	v_mul_f32_e32 v88, v87, v69
	v_mul_f32_e32 v76, v85, v88
	v_fma_f32 v80, v88, v85, -v76
	v_fmac_f32_e32 v80, v88, v86
	v_sub_f32_e32 v77, v77, v69
	v_add_f32_e32 v85, v68, v77
	v_add_f32_e32 v68, v76, v80
	v_sub_f32_e32 v77, v69, v68
	v_pk_add_f32 v[82:83], v[68:69], v[76:77] neg_lo:[0,1] neg_hi:[0,1]
	v_mov_b32_e32 v81, v68
	v_pk_add_f32 v[68:69], v[82:83], v[80:81] neg_lo:[0,1] neg_hi:[0,1]
	s_nop 0
	v_add_f32_e32 v69, v85, v69
	v_add_f32_e32 v68, v68, v69
	v_add_f32_e32 v69, v89, v88
	v_add_f32_e32 v68, v77, v68
	v_sub_f32_e32 v76, v69, v89
	v_mul_f32_e32 v68, v87, v68
	v_sub_f32_e32 v76, v88, v76
	v_add_f32_e32 v76, v76, v68
	v_add_f32_e32 v80, v69, v76
	v_mul_f32_e32 v81, v80, v80
	v_fmamk_f32 v68, v81, 0x3e9b6dac, v110
	v_fmaak_f32 v99, v81, v68, 0x3f2aaada
	v_cvt_f32_i32_e32 v68, v84
	v_sub_f32_e32 v69, v80, v69
	v_sub_f32_e32 v69, v76, v69
	v_ldexp_f32 v82, v69, 1
	v_mul_f32_e32 v69, v80, v81
	v_ldexp_f32 v77, v80, 1
	v_pk_mul_f32 v[80:81], v[68:69], v[98:99]
	s_nop 0
	v_fma_f32 v76, v68, s59, -v80
	v_fmac_f32_e32 v76, 0xb102e308, v68
	v_pk_add_f32 v[68:69], v[80:81], v[76:77]
	s_nop 0
	v_sub_f32_e32 v77, v69, v77
	v_sub_f32_e32 v77, v81, v77
	v_add_f32_e32 v83, v82, v77
	v_mov_b32_e32 v82, v80
	v_pk_add_f32 v[80:81], v[68:69], v[80:81] neg_lo:[0,1] neg_hi:[0,1]
	v_pk_add_f32 v[84:85], v[68:69], v[82:83]
	v_mov_b32_e32 v77, v68
	v_mov_b32_e32 v81, v85
	v_pk_add_f32 v[86:87], v[76:77], v[80:81] neg_lo:[0,1] neg_hi:[0,1]
	v_pk_add_f32 v[76:77], v[76:77], v[80:81]
	v_mov_b32_e32 v82, v83
	v_pk_add_f32 v[80:81], v[76:77], v[68:69] op_sel:[1,0] op_sel_hi:[0,1] neg_lo:[0,1] neg_hi:[0,1]
	v_pk_add_f32 v[88:89], v[84:85], v[80:81] op_sel_hi:[1,0] neg_lo:[0,1] neg_hi:[0,1]
	v_mov_b32_e32 v84, v85
	v_mov_b32_e32 v85, v77
	v_pk_mov_b32 v[80:81], v[68:69], v[80:81] op_sel:[1,0]
	v_mov_b32_e32 v83, v68
	v_pk_add_f32 v[80:81], v[84:85], v[80:81] neg_lo:[0,1] neg_hi:[0,1]
	v_mov_b32_e32 v88, v86
	v_pk_add_f32 v[68:69], v[82:83], v[80:81] neg_lo:[0,1] neg_hi:[0,1]
	v_mov_b32_e32 v87, v77
	v_pk_add_f32 v[80:81], v[88:89], v[68:69]
	s_nop 0
	v_pk_add_f32 v[82:83], v[80:81], v[80:81] op_sel:[0,1] op_sel_hi:[1,0]
	s_nop 0
	v_pk_add_f32 v[76:77], v[76:77], v[82:83] op_sel:[1,0] op_sel_hi:[0,1]
	v_mov_b32_e32 v81, v76
	v_pk_add_f32 v[84:85], v[80:81], v[86:87] neg_lo:[0,1] neg_hi:[0,1]
	v_mov_b32_e32 v69, v82
	v_sub_f32_e32 v77, v80, v84
	v_pk_add_f32 v[68:69], v[68:69], v[84:85] neg_lo:[0,1] neg_hi:[0,1]
	v_sub_f32_e32 v77, v86, v77
	v_add_f32_e32 v68, v68, v77
	v_add_f32_e32 v68, v68, v69
	v_add_f32_e32 v68, v76, v68
	v_cndmask_b32_e32 v68, v114, v68, vcc
	v_cmp_ngt_f32_e32 vcc, -1.0, v70
	s_nop 1
	v_cndmask_b32_e32 v68, v115, v68, vcc
	v_cmp_neq_f32_e32 vcc, -1.0, v70
	s_nop 1
	v_cndmask_b32_e32 v68, v116, v68, vcc
	v_cmp_lt_f32_e64 vcc, |v70|, s61
	s_nop 1
	v_cndmask_b32_e32 v68, v68, v70, vcc
.LBB0_127:
	s_or_b64 exec, exec, s[42:43]
	v_mov_b32_e32 v69, s94
	s_nop 0
	v_mul_f32_e32 v69, 0x3fb8aa3b, v69
	v_exp_f32_e32 v69, v69
	s_nop 0
	v_mul_f32_e64 v76, v68, -v69
	v_mov_b64_e32 v[68:69], 0xee9e000

; __device__ __forceinline__ void phase1(const Params& p, unsigned char* smem) {
;     ...
;             else { float z = v[h] + p.dt_bias[h]; float sp = z > 20.f ? z : log1pf(__expf(z)); GG[o] = -__expf(p.a_log[h]) * sp; }
.LBB0_130:
	s_or_saveexec_b64 s[40:41], s[40:41]
	v_mov_b64_e32 v[68:69], 0xee1d000
	s_xor_b64 exec, exec, s[40:41]
	s_cbranch_execz .LBB0_134
	v_mov_b32_e32 v68, s79
	s_nop 0
	v_add_f32_e32 v68, v71, v68
	v_cmp_nlt_f32_e32 vcc, s57, v68
	s_and_saveexec_b64 s[42:43], vcc
	s_cbranch_execz .LBB0_133
	v_mul_f32_e32 v68, 0x3fb8aa3b, v68
	v_exp_f32_e32 v88, v68
	s_nop 0
	v_add_f32_e32 v70, 1.0, v88
	v_frexp_mant_f32_e32 v76, v70
	v_cvt_f64_f32_e32 v[68:69], v70
	v_frexp_exp_i32_f64_e32 v68, v[68:69]
	v_cmp_gt_f32_e32 vcc, s58, v76
	v_add_f32_e32 v71, -1.0, v70
	v_sub_f32_e32 v77, v71, v70
	v_subbrev_co_u32_e32 v82, vcc, 0, v68, vcc
	v_sub_u32_e32 v68, 0, v82
	v_sub_f32_e32 v71, v88, v71
	v_add_f32_e32 v77, 1.0, v77
	v_ldexp_f32 v69, v70, v68
	v_add_f32_e32 v71, v71, v77
	v_add_f32_e32 v70, -1.0, v69
	v_add_f32_e32 v76, 1.0, v69
	v_ldexp_f32 v68, v71, v68
	v_add_f32_e32 v71, 1.0, v70
	v_add_f32_e32 v77, -1.0, v76
	v_sub_f32_e32 v71, v69, v71
	v_sub_f32_e32 v69, v69, v77
	v_add_f32_e32 v71, v68, v71
	v_add_f32_e32 v68, v68, v69
	v_add_f32_e32 v83, v76, v68
	v_rcp_f32_e32 v85, v83
	v_sub_f32_e32 v69, v83, v76
	v_sub_f32_e32 v84, v68, v69
	v_add_f32_e32 v69, v70, v71
	v_mul_f32_e32 v87, v69, v85
	v_sub_f32_e32 v68, v69, v70
	v_mul_f32_e32 v70, v83, v87
	v_fma_f32 v76, v87, v83, -v70
	v_fmac_f32_e32 v76, v87, v84
	v_sub_f32_e32 v86, v71, v68
	v_add_f32_e32 v68, v70, v76
	v_sub_f32_e32 v71, v69, v68
	v_pk_add_f32 v[80:81], v[68:69], v[70:71] neg_lo:[0,1] neg_hi:[0,1]
	v_mov_b32_e32 v77, v68
	v_pk_add_f32 v[68:69], v[80:81], v[76:77] neg_lo:[0,1] neg_hi:[0,1]
	v_cmp_neq_f32_e32 vcc, s60, v88
	v_add_f32_e32 v69, v86, v69
	v_add_f32_e32 v68, v68, v69
	v_add_f32_e32 v69, v71, v68
	v_mul_f32_e32 v86, v85, v69
	v_mul_f32_e32 v70, v83, v86
	v_fma_f32 v76, v86, v83, -v70
	v_fmac_f32_e32 v76, v86, v84
	v_sub_f32_e32 v71, v71, v69
	v_add_f32_e32 v83, v68, v71
	v_add_f32_e32 v68, v70, v76
	v_sub_f32_e32 v71, v69, v68
	v_pk_add_f32 v[80:81], v[68:69], v[70:71] neg_lo:[0,1] neg_hi:[0,1]
	v_mov_b32_e32 v77, v68
	v_pk_add_f32 v[68:69], v[80:81], v[76:77] neg_lo:[0,1] neg_hi:[0,1]
	s_nop 0
	v_add_f32_e32 v69, v83, v69
	v_add_f32_e32 v68, v68, v69
	v_add_f32_e32 v69, v87, v86
	v_add_f32_e32 v68, v71, v68
	v_sub_f32_e32 v70, v69, v87
	v_mul_f32_e32 v68, v85, v68
	v_sub_f32_e32 v70, v86, v70
	v_add_f32_e32 v70, v70, v68
	v_add_f32_e32 v76, v69, v70
	v_mul_f32_e32 v77, v76, v76
	v_fmamk_f32 v68, v77, 0x3e9b6dac, v110
	v_fmaak_f32 v99, v77, v68, 0x3f2aaada
	v_cvt_f32_i32_e32 v68, v82
	v_sub_f32_e32 v69, v76, v69
	v_sub_f32_e32 v69, v70, v69
	v_ldexp_f32 v80, v69, 1
	v_mul_f32_e32 v69, v76, v77
	v_ldexp_f32 v71, v76, 1
	v_pk_mul_f32 v[76:77], v[68:69], v[98:99]
	s_nop 0
	v_fma_f32 v70, v68, s59, -v76
	v_fmac_f32_e32 v70, 0xb102e308, v68
	v_pk_add_f32 v[68:69], v[76:77], v[70:71]
	s_nop 0
	v_sub_f32_e32 v71, v69, v71
	v_sub_f32_e32 v71, v77, v71
	v_add_f32_e32 v81, v80, v71
	v_mov_b32_e32 v80, v76
	v_pk_add_f32 v[76:77], v[68:69], v[76:77] neg_lo:[0,1] neg_hi:[0,1]
	v_pk_add_f32 v[82:83], v[68:69], v[80:81]
	v_mov_b32_e32 v71, v68
	v_mov_b32_e32 v77, v83
	v_pk_add_f32 v[84:85], v[70:71], v[76:77] neg_lo:[0,1] neg_hi:[0,1]
	v_pk_add_f32 v[70:71], v[70:71], v[76:77]
	v_mov_b32_e32 v80, v81
	v_pk_add_f32 v[76:77], v[70:71], v[68:69] op_sel:[1,0] op_sel_hi:[0,1] neg_lo:[0,1] neg_hi:[0,1]
	v_pk_add_f32 v[86:87], v[82:83], v[76:77] op_sel_hi:[1,0] neg_lo:[0,1] neg_hi:[0,1]
	v_mov_b32_e32 v82, v83
	v_mov_b32_e32 v83, v71
	v_pk_mov_b32 v[76:77], v[68:69], v[76:77] op_sel:[1,0]
	v_mov_b32_e32 v81, v68
	v_pk_add_f32 v[76:77], v[82:83], v[76:77] neg_lo:[0,1] neg_hi:[0,1]
	v_mov_b32_e32 v86, v84
	v_pk_add_f32 v[68:69], v[80:81], v[76:77] neg_lo:[0,1] neg_hi:[0,1]
	v_mov_b32_e32 v85, v71
	v_pk_add_f32 v[76:77], v[86:87], v[68:69]
	s_nop 0
	v_pk_add_f32 v[80:81], v[76:77], v[76:77] op_sel:[0,1] op_sel_hi:[1,0]
	s_nop 0
	v_pk_add_f32 v[70:71], v[70:71], v[80:81] op_sel:[1,0] op_sel_hi:[0,1]
	v_mov_b32_e32 v77, v70
	v_pk_add_f32 v[82:83], v[76:77], v[84:85] neg_lo:[0,1] neg_hi:[0,1]
	v_mov_b32_e32 v69, v80
	v_sub_f32_e32 v71, v76, v82
	v_pk_add_f32 v[68:69], v[68:69], v[82:83] neg_lo:[0,1] neg_hi:[0,1]
	v_sub_f32_e32 v71, v84, v71
	v_add_f32_e32 v68, v68, v71
	v_add_f32_e32 v68, v68, v69
	v_add_f32_e32 v68, v70, v68
	v_cndmask_b32_e32 v68, v114, v68, vcc
	v_cmp_ngt_f32_e32 vcc, -1.0, v88
	s_nop 1
	v_cndmask_b32_e32 v68, v115, v68, vcc
	v_cmp_neq_f32_e32 vcc, -1.0, v88
	s_nop 1
	v_cndmask_b32_e32 v68, v116, v68, vcc
	v_cmp_lt_f32_e64 vcc, |v88|, s61
	s_nop 1
	v_cndmask_b32_e32 v68, v68, v88, vcc
.LBB0_133:
	s_or_b64 exec, exec, s[42:43]
	v_mov_b32_e32 v69, s95
	s_nop 0
	v_mul_f32_e32 v69, 0x3fb8aa3b, v69
	v_exp_f32_e32 v69, v69
	s_nop 0
	v_mul_f32_e64 v76, v68, -v69
	v_mov_b64_e32 v[68:69], 0xee9e000

; __device__ __forceinline__ void phase1(const Params& p, unsigned char* smem) {
;     ...
;             else { float z = v[h] + p.dt_bias[h]; float sp = z > 20.f ? z : log1pf(__expf(z)); GG[o] = -__expf(p.a_log[h]) * sp; }
.LBB0_136:
	s_or_saveexec_b64 s[40:41], s[40:41]
	v_mov_b64_e32 v[68:69], 0xee1d000
	s_xor_b64 exec, exec, s[40:41]
	s_cbranch_execz .LBB0_140
	v_mov_b32_e32 v68, s80
	s_waitcnt lgkmcnt(0)
	v_add_f32_e32 v64, v64, v68
	v_cmp_nlt_f32_e32 vcc, s57, v64
	s_and_saveexec_b64 s[42:43], vcc
	s_cbranch_execz .LBB0_139
	v_mul_f32_e32 v64, 0x3fb8aa3b, v64
	v_exp_f32_e32 v64, v64
	s_nop 0
	v_add_f32_e32 v70, 1.0, v64
	v_frexp_mant_f32_e32 v76, v70
	v_cvt_f64_f32_e32 v[68:69], v70
	v_frexp_exp_i32_f64_e32 v68, v[68:69]
	v_cmp_gt_f32_e32 vcc, s58, v76
	v_add_f32_e32 v71, -1.0, v70
	v_sub_f32_e32 v77, v71, v70
	v_subbrev_co_u32_e32 v82, vcc, 0, v68, vcc
	v_sub_u32_e32 v68, 0, v82
	v_sub_f32_e32 v71, v64, v71
	v_add_f32_e32 v77, 1.0, v77
	v_ldexp_f32 v69, v70, v68
	v_add_f32_e32 v71, v71, v77
	v_add_f32_e32 v70, -1.0, v69
	v_add_f32_e32 v76, 1.0, v69
	v_ldexp_f32 v68, v71, v68
	v_add_f32_e32 v71, 1.0, v70
	v_add_f32_e32 v77, -1.0, v76
	v_sub_f32_e32 v71, v69, v71
	v_sub_f32_e32 v69, v69, v77
	v_add_f32_e32 v71, v68, v71
	v_add_f32_e32 v68, v68, v69
	v_add_f32_e32 v83, v76, v68
	v_rcp_f32_e32 v85, v83
	v_sub_f32_e32 v69, v83, v76
	v_sub_f32_e32 v84, v68, v69
	v_add_f32_e32 v69, v70, v71
	v_mul_f32_e32 v87, v69, v85
	v_sub_f32_e32 v68, v69, v70
	v_mul_f32_e32 v70, v83, v87
	v_fma_f32 v76, v87, v83, -v70
	v_fmac_f32_e32 v76, v87, v84
	v_sub_f32_e32 v86, v71, v68
	v_add_f32_e32 v68, v70, v76
	v_sub_f32_e32 v71, v69, v68
	v_pk_add_f32 v[80:81], v[68:69], v[70:71] neg_lo:[0,1] neg_hi:[0,1]
	v_mov_b32_e32 v77, v68
	v_pk_add_f32 v[68:69], v[80:81], v[76:77] neg_lo:[0,1] neg_hi:[0,1]
	v_cmp_neq_f32_e32 vcc, s60, v64
	v_add_f32_e32 v69, v86, v69
	v_add_f32_e32 v68, v68, v69
	v_add_f32_e32 v69, v71, v68
	v_mul_f32_e32 v86, v85, v69
	v_mul_f32_e32 v70, v83, v86
	v_fma_f32 v76, v86, v83, -v70
	v_fmac_f32_e32 v76, v86, v84
	v_sub_f32_e32 v71, v71, v69
	v_add_f32_e32 v83, v68, v71
	v_add_f32_e32 v68, v70, v76
	v_sub_f32_e32 v71, v69, v68
	v_pk_add_f32 v[80:81], v[68:69], v[70:71] neg_lo:[0,1] neg_hi:[0,1]
	v_mov_b32_e32 v77, v68
	v_pk_add_f32 v[68:69], v[80:81], v[76:77] neg_lo:[0,1] neg_hi:[0,1]
	s_nop 0
	v_add_f32_e32 v69, v83, v69
	v_add_f32_e32 v68, v68, v69
	v_add_f32_e32 v69, v87, v86
	v_add_f32_e32 v68, v71, v68
	v_sub_f32_e32 v70, v69, v87
	v_mul_f32_e32 v68, v85, v68
	v_sub_f32_e32 v70, v86, v70
	v_add_f32_e32 v70, v70, v68
	v_add_f32_e32 v76, v69, v70
	v_mul_f32_e32 v77, v76, v76
	v_fmamk_f32 v68, v77, 0x3e9b6dac, v110
	v_fmaak_f32 v99, v77, v68, 0x3f2aaada
	v_cvt_f32_i32_e32 v68, v82
	v_sub_f32_e32 v69, v76, v69
	v_sub_f32_e32 v69, v70, v69
	v_ldexp_f32 v80, v69, 1
	v_mul_f32_e32 v69, v76, v77
	v_ldexp_f32 v71, v76, 1
	v_pk_mul_f32 v[76:77], v[68:69], v[98:99]
	s_nop 0
	v_fma_f32 v70, v68, s59, -v76
	v_fmac_f32_e32 v70, 0xb102e308, v68
	v_pk_add_f32 v[68:69], v[76:77], v[70:71]
	s_nop 0
	v_sub_f32_e32 v71, v69, v71
	v_sub_f32_e32 v71, v77, v71
	v_add_f32_e32 v81, v80, v71
	v_mov_b32_e32 v80, v76
	v_pk_add_f32 v[76:77], v[68:69], v[76:77] neg_lo:[0,1] neg_hi:[0,1]
	v_pk_add_f32 v[82:83], v[68:69], v[80:81]
	v_mov_b32_e32 v71, v68
	v_mov_b32_e32 v77, v83
	v_pk_add_f32 v[84:85], v[70:71], v[76:77] neg_lo:[0,1] neg_hi:[0,1]
	v_pk_add_f32 v[70:71], v[70:71], v[76:77]
	v_mov_b32_e32 v80, v81
	v_pk_add_f32 v[76:77], v[70:71], v[68:69] op_sel:[1,0] op_sel_hi:[0,1] neg_lo:[0,1] neg_hi:[0,1]
	v_pk_add_f32 v[86:87], v[82:83], v[76:77] op_sel_hi:[1,0] neg_lo:[0,1] neg_hi:[0,1]
	v_mov_b32_e32 v82, v83
	v_mov_b32_e32 v83, v71
	v_pk_mov_b32 v[76:77], v[68:69], v[76:77] op_sel:[1,0]
	v_mov_b32_e32 v81, v68
	v_pk_add_f32 v[76:77], v[82:83], v[76:77] neg_lo:[0,1] neg_hi:[0,1]
	v_mov_b32_e32 v86, v84
	v_pk_add_f32 v[68:69], v[80:81], v[76:77] neg_lo:[0,1] neg_hi:[0,1]
	v_mov_b32_e32 v85, v71
	v_pk_add_f32 v[76:77], v[86:87], v[68:69]
	s_nop 0
	v_pk_add_f32 v[80:81], v[76:77], v[76:77] op_sel:[0,1] op_sel_hi:[1,0]
	s_nop 0
	v_pk_add_f32 v[70:71], v[70:71], v[80:81] op_sel:[1,0] op_sel_hi:[0,1]
	v_mov_b32_e32 v77, v70
	v_pk_add_f32 v[82:83], v[76:77], v[84:85] neg_lo:[0,1] neg_hi:[0,1]
	v_mov_b32_e32 v69, v80
	v_sub_f32_e32 v71, v76, v82
	v_pk_add_f32 v[68:69], v[68:69], v[82:83] neg_lo:[0,1] neg_hi:[0,1]
	v_sub_f32_e32 v71, v84, v71
	v_add_f32_e32 v68, v68, v71
	v_add_f32_e32 v68, v68, v69
	v_add_f32_e32 v68, v70, v68
	v_cndmask_b32_e32 v68, v114, v68, vcc
	v_cmp_ngt_f32_e32 vcc, -1.0, v64
	s_nop 1
	v_cndmask_b32_e32 v68, v115, v68, vcc
	v_cmp_neq_f32_e32 vcc, -1.0, v64
	s_nop 1
	v_cndmask_b32_e32 v68, v116, v68, vcc
	v_cmp_lt_f32_e64 vcc, |v64|, s61
	s_nop 1
	v_cndmask_b32_e32 v64, v68, v64, vcc
.LBB0_139:
	s_or_b64 exec, exec, s[42:43]
	v_mov_b32_e32 v68, s96
	s_nop 0
	v_mul_f32_e32 v68, 0x3fb8aa3b, v68
	v_exp_f32_e32 v68, v68
	s_nop 0
	v_mul_f32_e64 v70, v64, -v68
	v_mov_b64_e32 v[68:69], 0xee9e000

; __device__ __forceinline__ void phase1(const Params& p, unsigned char* smem) {
;     ...
;             else { float z = v[h] + p.dt_bias[h]; float sp = z > 20.f ? z : log1pf(__expf(z)); GG[o] = -__expf(p.a_log[h]) * sp; }
.LBB0_142:
	s_or_saveexec_b64 s[40:41], s[40:41]
	v_mov_b64_e32 v[68:69], 0xee1d000
	s_xor_b64 exec, exec, s[40:41]
	s_cbranch_execz .LBB0_146
	v_mov_b32_e32 v64, s81
	s_nop 0
	v_add_f32_e32 v64, v65, v64
	v_cmp_nlt_f32_e32 vcc, s57, v64
	s_and_saveexec_b64 s[42:43], vcc
	s_cbranch_execz .LBB0_145
	v_mul_f32_e32 v64, 0x3fb8aa3b, v64
	v_exp_f32_e32 v86, v64
	s_nop 0
	v_add_f32_e32 v68, 1.0, v86
	v_frexp_mant_f32_e32 v70, v68
	v_cvt_f64_f32_e32 v[64:65], v68
	v_frexp_exp_i32_f64_e32 v64, v[64:65]
	v_cmp_gt_f32_e32 vcc, s58, v70
	v_add_f32_e32 v69, -1.0, v68
	v_sub_f32_e32 v71, v69, v68
	v_subbrev_co_u32_e32 v80, vcc, 0, v64, vcc
	v_sub_u32_e32 v64, 0, v80
	v_sub_f32_e32 v69, v86, v69
	v_add_f32_e32 v71, 1.0, v71
	v_ldexp_f32 v65, v68, v64
	v_add_f32_e32 v69, v69, v71
	v_add_f32_e32 v68, -1.0, v65
	v_add_f32_e32 v70, 1.0, v65
	v_ldexp_f32 v64, v69, v64
	v_add_f32_e32 v69, 1.0, v68
	v_add_f32_e32 v71, -1.0, v70
	v_sub_f32_e32 v69, v65, v69
	v_sub_f32_e32 v65, v65, v71
	v_add_f32_e32 v69, v64, v69
	v_add_f32_e32 v64, v64, v65
	v_add_f32_e32 v81, v70, v64
	v_rcp_f32_e32 v83, v81
	v_sub_f32_e32 v65, v81, v70
	v_sub_f32_e32 v82, v64, v65
	v_add_f32_e32 v65, v68, v69
	v_mul_f32_e32 v85, v65, v83
	v_sub_f32_e32 v64, v65, v68
	v_mul_f32_e32 v68, v81, v85
	v_fma_f32 v70, v85, v81, -v68
	v_fmac_f32_e32 v70, v85, v82
	v_sub_f32_e32 v84, v69, v64
	v_add_f32_e32 v64, v68, v70
	v_sub_f32_e32 v69, v65, v64
	v_pk_add_f32 v[76:77], v[64:65], v[68:69] neg_lo:[0,1] neg_hi:[0,1]
	v_mov_b32_e32 v71, v64
	v_pk_add_f32 v[64:65], v[76:77], v[70:71] neg_lo:[0,1] neg_hi:[0,1]
	v_cmp_neq_f32_e32 vcc, s60, v86
	v_add_f32_e32 v65, v84, v65
	v_add_f32_e32 v64, v64, v65
	v_add_f32_e32 v65, v69, v64
	v_mul_f32_e32 v84, v83, v65
	v_mul_f32_e32 v68, v81, v84
	v_fma_f32 v70, v84, v81, -v68
	v_fmac_f32_e32 v70, v84, v82
	v_sub_f32_e32 v69, v69, v65
	v_add_f32_e32 v81, v64, v69
	v_add_f32_e32 v64, v68, v70
	v_sub_f32_e32 v69, v65, v64
	v_pk_add_f32 v[76:77], v[64:65], v[68:69] neg_lo:[0,1] neg_hi:[0,1]
	v_mov_b32_e32 v71, v64
	v_pk_add_f32 v[64:65], v[76:77], v[70:71] neg_lo:[0,1] neg_hi:[0,1]
	s_nop 0
	v_add_f32_e32 v65, v81, v65
	v_add_f32_e32 v64, v64, v65
	v_add_f32_e32 v65, v85, v84
	v_add_f32_e32 v64, v69, v64
	v_sub_f32_e32 v68, v65, v85
	v_mul_f32_e32 v64, v83, v64
	v_sub_f32_e32 v68, v84, v68
	v_add_f32_e32 v68, v68, v64
	v_add_f32_e32 v70, v65, v68
	v_mul_f32_e32 v71, v70, v70
	v_fmamk_f32 v64, v71, 0x3e9b6dac, v110
	v_fmaak_f32 v99, v71, v64, 0x3f2aaada
	v_cvt_f32_i32_e32 v64, v80
	v_sub_f32_e32 v65, v70, v65
	v_sub_f32_e32 v65, v68, v65
	v_ldexp_f32 v76, v65, 1
	v_mul_f32_e32 v65, v70, v71
	v_ldexp_f32 v69, v70, 1
	v_pk_mul_f32 v[70:71], v[64:65], v[98:99]
	s_nop 0
	v_fma_f32 v68, v64, s59, -v70
	v_fmac_f32_e32 v68, 0xb102e308, v64
	v_pk_add_f32 v[64:65], v[70:71], v[68:69]
	s_nop 0
	v_sub_f32_e32 v69, v65, v69
	v_sub_f32_e32 v69, v71, v69
	v_add_f32_e32 v77, v76, v69
	v_mov_b32_e32 v76, v70
	v_pk_add_f32 v[70:71], v[64:65], v[70:71] neg_lo:[0,1] neg_hi:[0,1]
	v_pk_add_f32 v[80:81], v[64:65], v[76:77]
	v_mov_b32_e32 v69, v64
	v_mov_b32_e32 v71, v81
	v_pk_add_f32 v[82:83], v[68:69], v[70:71] neg_lo:[0,1] neg_hi:[0,1]
	v_pk_add_f32 v[68:69], v[68:69], v[70:71]
	v_mov_b32_e32 v76, v77
	v_pk_add_f32 v[70:71], v[68:69], v[64:65] op_sel:[1,0] op_sel_hi:[0,1] neg_lo:[0,1] neg_hi:[0,1]
	v_pk_add_f32 v[84:85], v[80:81], v[70:71] op_sel_hi:[1,0] neg_lo:[0,1] neg_hi:[0,1]
	v_mov_b32_e32 v80, v81
	v_mov_b32_e32 v81, v69
	v_pk_mov_b32 v[70:71], v[64:65], v[70:71] op_sel:[1,0]
	v_mov_b32_e32 v77, v64
	v_pk_add_f32 v[70:71], v[80:81], v[70:71] neg_lo:[0,1] neg_hi:[0,1]
	v_mov_b32_e32 v84, v82
	v_pk_add_f32 v[64:65], v[76:77], v[70:71] neg_lo:[0,1] neg_hi:[0,1]
	v_mov_b32_e32 v83, v69
	v_pk_add_f32 v[70:71], v[84:85], v[64:65]
	s_nop 0
	v_pk_add_f32 v[76:77], v[70:71], v[70:71] op_sel:[0,1] op_sel_hi:[1,0]
	s_nop 0
	v_pk_add_f32 v[68:69], v[68:69], v[76:77] op_sel:[1,0] op_sel_hi:[0,1]
	v_mov_b32_e32 v71, v68
	v_pk_add_f32 v[80:81], v[70:71], v[82:83] neg_lo:[0,1] neg_hi:[0,1]
	v_mov_b32_e32 v65, v76
	v_sub_f32_e32 v69, v70, v80
	v_pk_add_f32 v[64:65], v[64:65], v[80:81] neg_lo:[0,1] neg_hi:[0,1]
	v_sub_f32_e32 v69, v82, v69
	v_add_f32_e32 v64, v64, v69
	v_add_f32_e32 v64, v64, v65
	v_add_f32_e32 v64, v68, v64
	v_cndmask_b32_e32 v64, v114, v64, vcc
	v_cmp_ngt_f32_e32 vcc, -1.0, v86
	s_nop 1
	v_cndmask_b32_e32 v64, v115, v64, vcc
	v_cmp_neq_f32_e32 vcc, -1.0, v86
	s_nop 1
	v_cndmask_b32_e32 v64, v116, v64, vcc
	v_cmp_lt_f32_e64 vcc, |v86|, s61
	s_nop 1
	v_cndmask_b32_e32 v64, v64, v86, vcc
.LBB0_145:
	s_or_b64 exec, exec, s[42:43]
	v_mov_b32_e32 v65, s97
	v_mov_b64_e32 v[68:69], 0xee9e000
	s_nop 0
	v_mul_f32_e32 v65, 0x3fb8aa3b, v65
	v_exp_f32_e32 v65, v65
	s_nop 0
	v_mul_f32_e64 v64, v64, -v65

; __device__ __forceinline__ void phase1(const Params& p, unsigned char* smem) {
;     ...
;             else { float z = v[h] + p.dt_bias[h]; float sp = z > 20.f ? z : log1pf(__expf(z)); GG[o] = -__expf(p.a_log[h]) * sp; }
.LBB0_148:
	s_or_saveexec_b64 s[40:41], s[40:41]
	v_mov_b64_e32 v[64:65], 0xee1d000
	s_xor_b64 exec, exec, s[40:41]
	s_cbranch_execz .LBB0_152
	v_mov_b32_e32 v64, s82
	s_nop 0
	v_add_f32_e32 v64, v66, v64
	v_cmp_nlt_f32_e32 vcc, s57, v64
	s_and_saveexec_b64 s[42:43], vcc
	s_cbranch_execz .LBB0_151
	v_mul_f32_e32 v64, 0x3fb8aa3b, v64
	v_exp_f32_e32 v66, v64
	s_nop 0
	v_add_f32_e32 v68, 1.0, v66
	v_frexp_mant_f32_e32 v70, v68
	v_cvt_f64_f32_e32 v[64:65], v68
	v_frexp_exp_i32_f64_e32 v64, v[64:65]
	v_cmp_gt_f32_e32 vcc, s58, v70
	v_add_f32_e32 v69, -1.0, v68
	v_sub_f32_e32 v71, v69, v68
	v_subbrev_co_u32_e32 v80, vcc, 0, v64, vcc
	v_sub_u32_e32 v64, 0, v80
	v_sub_f32_e32 v69, v66, v69
	v_add_f32_e32 v71, 1.0, v71
	v_ldexp_f32 v65, v68, v64
	v_add_f32_e32 v69, v69, v71
	v_add_f32_e32 v68, -1.0, v65
	v_add_f32_e32 v70, 1.0, v65
	v_ldexp_f32 v64, v69, v64
	v_add_f32_e32 v69, 1.0, v68
	v_add_f32_e32 v71, -1.0, v70
	v_sub_f32_e32 v69, v65, v69
	v_sub_f32_e32 v65, v65, v71
	v_add_f32_e32 v69, v64, v69
	v_add_f32_e32 v64, v64, v65
	v_add_f32_e32 v81, v70, v64
	v_rcp_f32_e32 v83, v81
	v_sub_f32_e32 v65, v81, v70
	v_sub_f32_e32 v82, v64, v65
	v_add_f32_e32 v65, v68, v69
	v_mul_f32_e32 v85, v65, v83
	v_sub_f32_e32 v64, v65, v68
	v_mul_f32_e32 v68, v81, v85
	v_fma_f32 v70, v85, v81, -v68
	v_fmac_f32_e32 v70, v85, v82
	v_sub_f32_e32 v84, v69, v64
	v_add_f32_e32 v64, v68, v70
	v_sub_f32_e32 v69, v65, v64
	v_pk_add_f32 v[76:77], v[64:65], v[68:69] neg_lo:[0,1] neg_hi:[0,1]
	v_mov_b32_e32 v71, v64
	v_pk_add_f32 v[64:65], v[76:77], v[70:71] neg_lo:[0,1] neg_hi:[0,1]
	v_cmp_neq_f32_e32 vcc, s60, v66
	v_add_f32_e32 v65, v84, v65
	v_add_f32_e32 v64, v64, v65
	v_add_f32_e32 v65, v69, v64
	v_mul_f32_e32 v84, v83, v65
	v_mul_f32_e32 v68, v81, v84
	v_fma_f32 v70, v84, v81, -v68
	v_fmac_f32_e32 v70, v84, v82
	v_sub_f32_e32 v69, v69, v65
	v_add_f32_e32 v81, v64, v69
	v_add_f32_e32 v64, v68, v70
	v_sub_f32_e32 v69, v65, v64
	v_pk_add_f32 v[76:77], v[64:65], v[68:69] neg_lo:[0,1] neg_hi:[0,1]
	v_mov_b32_e32 v71, v64
	v_pk_add_f32 v[64:65], v[76:77], v[70:71] neg_lo:[0,1] neg_hi:[0,1]
	s_nop 0
	v_add_f32_e32 v65, v81, v65
	v_add_f32_e32 v64, v64, v65
	v_add_f32_e32 v65, v85, v84
	v_add_f32_e32 v64, v69, v64
	v_sub_f32_e32 v68, v65, v85
	v_mul_f32_e32 v64, v83, v64
	v_sub_f32_e32 v68, v84, v68
	v_add_f32_e32 v68, v68, v64
	v_add_f32_e32 v70, v65, v68
	v_mul_f32_e32 v71, v70, v70
	v_fmamk_f32 v64, v71, 0x3e9b6dac, v110
	v_fmaak_f32 v99, v71, v64, 0x3f2aaada
	v_cvt_f32_i32_e32 v64, v80
	v_sub_f32_e32 v65, v70, v65
	v_sub_f32_e32 v65, v68, v65
	v_ldexp_f32 v76, v65, 1
	v_mul_f32_e32 v65, v70, v71
	v_ldexp_f32 v69, v70, 1
	v_pk_mul_f32 v[70:71], v[64:65], v[98:99]
	s_nop 0
	v_fma_f32 v68, v64, s59, -v70
	v_fmac_f32_e32 v68, 0xb102e308, v64
	v_pk_add_f32 v[64:65], v[70:71], v[68:69]
	s_nop 0
	v_sub_f32_e32 v69, v65, v69
	v_sub_f32_e32 v69, v71, v69
	v_add_f32_e32 v77, v76, v69
	v_mov_b32_e32 v76, v70
	v_pk_add_f32 v[70:71], v[64:65], v[70:71] neg_lo:[0,1] neg_hi:[0,1]
	v_pk_add_f32 v[80:81], v[64:65], v[76:77]
	v_mov_b32_e32 v69, v64
	v_mov_b32_e32 v71, v81
	v_pk_add_f32 v[82:83], v[68:69], v[70:71] neg_lo:[0,1] neg_hi:[0,1]
	v_pk_add_f32 v[68:69], v[68:69], v[70:71]
	v_mov_b32_e32 v76, v77
	v_pk_add_f32 v[70:71], v[68:69], v[64:65] op_sel:[1,0] op_sel_hi:[0,1] neg_lo:[0,1] neg_hi:[0,1]
	v_pk_add_f32 v[84:85], v[80:81], v[70:71] op_sel_hi:[1,0] neg_lo:[0,1] neg_hi:[0,1]
	v_mov_b32_e32 v80, v81
	v_mov_b32_e32 v81, v69
	v_pk_mov_b32 v[70:71], v[64:65], v[70:71] op_sel:[1,0]
	v_mov_b32_e32 v77, v64
	v_pk_add_f32 v[70:71], v[80:81], v[70:71] neg_lo:[0,1] neg_hi:[0,1]
	v_mov_b32_e32 v84, v82
	v_pk_add_f32 v[64:65], v[76:77], v[70:71] neg_lo:[0,1] neg_hi:[0,1]
	v_mov_b32_e32 v83, v69
	v_pk_add_f32 v[70:71], v[84:85], v[64:65]
	s_nop 0
	v_pk_add_f32 v[76:77], v[70:71], v[70:71] op_sel:[0,1] op_sel_hi:[1,0]
	s_nop 0
	v_pk_add_f32 v[68:69], v[68:69], v[76:77] op_sel:[1,0] op_sel_hi:[0,1]
	v_mov_b32_e32 v71, v68
	v_pk_add_f32 v[80:81], v[70:71], v[82:83] neg_lo:[0,1] neg_hi:[0,1]
	v_mov_b32_e32 v65, v76
	v_sub_f32_e32 v69, v70, v80
	v_pk_add_f32 v[64:65], v[64:65], v[80:81] neg_lo:[0,1] neg_hi:[0,1]
	v_sub_f32_e32 v69, v82, v69
	v_add_f32_e32 v64, v64, v69
	v_add_f32_e32 v64, v64, v65
	v_add_f32_e32 v64, v68, v64
	v_cndmask_b32_e32 v64, v114, v64, vcc
	v_cmp_ngt_f32_e32 vcc, -1.0, v66
	s_nop 1
	v_cndmask_b32_e32 v64, v115, v64, vcc
	v_cmp_neq_f32_e32 vcc, -1.0, v66
	s_nop 1
	v_cndmask_b32_e32 v64, v116, v64, vcc
	v_cmp_lt_f32_e64 vcc, |v66|, s61
	s_nop 1
	v_cndmask_b32_e32 v64, v64, v66, vcc
.LBB0_151:
	s_or_b64 exec, exec, s[42:43]
	v_mov_b32_e32 v65, s98
	s_nop 0
	v_mul_f32_e32 v65, 0x3fb8aa3b, v65
	v_exp_f32_e32 v65, v65
	s_nop 0
	v_mul_f32_e64 v68, v64, -v65
	v_mov_b64_e32 v[64:65], 0xee9e000

; __device__ __forceinline__ void phase1(const Params& p, unsigned char* smem) {
;     ...
;             else { float z = v[h] + p.dt_bias[h]; float sp = z > 20.f ? z : log1pf(__expf(z)); GG[o] = -__expf(p.a_log[h]) * sp; }
.LBB0_154:
	s_or_saveexec_b64 s[40:41], s[40:41]
	v_mov_b64_e32 v[64:65], 0xee1d000
	s_xor_b64 exec, exec, s[40:41]
	s_cbranch_execz .LBB0_158
	v_mov_b32_e32 v64, s83
	s_nop 0
	v_add_f32_e32 v64, v67, v64
	v_cmp_nlt_f32_e32 vcc, s57, v64
	s_and_saveexec_b64 s[42:43], vcc
	s_cbranch_execz .LBB0_157
	v_mul_f32_e32 v64, 0x3fb8aa3b, v64
	v_exp_f32_e32 v84, v64
	s_nop 0
	v_add_f32_e32 v66, 1.0, v84
	v_frexp_mant_f32_e32 v68, v66
	v_cvt_f64_f32_e32 v[64:65], v66
	v_frexp_exp_i32_f64_e32 v64, v[64:65]
	v_cmp_gt_f32_e32 vcc, s58, v68
	v_add_f32_e32 v67, -1.0, v66
	v_sub_f32_e32 v69, v67, v66
	v_subbrev_co_u32_e32 v76, vcc, 0, v64, vcc
	v_sub_u32_e32 v64, 0, v76
	v_sub_f32_e32 v67, v84, v67
	v_add_f32_e32 v69, 1.0, v69
	v_ldexp_f32 v65, v66, v64
	v_add_f32_e32 v67, v67, v69
	v_add_f32_e32 v66, -1.0, v65
	v_add_f32_e32 v68, 1.0, v65
	v_ldexp_f32 v64, v67, v64
	v_add_f32_e32 v67, 1.0, v66
	v_add_f32_e32 v69, -1.0, v68
	v_sub_f32_e32 v67, v65, v67
	v_sub_f32_e32 v65, v65, v69
	v_add_f32_e32 v67, v64, v67
	v_add_f32_e32 v64, v64, v65
	v_add_f32_e32 v77, v68, v64
	v_rcp_f32_e32 v81, v77
	v_sub_f32_e32 v65, v77, v68
	v_sub_f32_e32 v80, v64, v65
	v_add_f32_e32 v65, v66, v67
	v_mul_f32_e32 v83, v65, v81
	v_sub_f32_e32 v64, v65, v66
	v_mul_f32_e32 v66, v77, v83
	v_fma_f32 v68, v83, v77, -v66
	v_fmac_f32_e32 v68, v83, v80
	v_sub_f32_e32 v82, v67, v64
	v_add_f32_e32 v64, v66, v68
	v_sub_f32_e32 v67, v65, v64
	v_pk_add_f32 v[70:71], v[64:65], v[66:67] neg_lo:[0,1] neg_hi:[0,1]
	v_mov_b32_e32 v69, v64
	v_pk_add_f32 v[64:65], v[70:71], v[68:69] neg_lo:[0,1] neg_hi:[0,1]
	v_cmp_neq_f32_e32 vcc, s60, v84
	v_add_f32_e32 v65, v82, v65
	v_add_f32_e32 v64, v64, v65
	v_add_f32_e32 v65, v67, v64
	v_mul_f32_e32 v82, v81, v65
	v_mul_f32_e32 v66, v77, v82
	v_fma_f32 v68, v82, v77, -v66
	v_fmac_f32_e32 v68, v82, v80
	v_sub_f32_e32 v67, v67, v65
	v_add_f32_e32 v77, v64, v67
	v_add_f32_e32 v64, v66, v68
	v_sub_f32_e32 v67, v65, v64
	v_pk_add_f32 v[70:71], v[64:65], v[66:67] neg_lo:[0,1] neg_hi:[0,1]
	v_mov_b32_e32 v69, v64
	v_pk_add_f32 v[64:65], v[70:71], v[68:69] neg_lo:[0,1] neg_hi:[0,1]
	s_nop 0
	v_add_f32_e32 v65, v77, v65
	v_add_f32_e32 v64, v64, v65
	v_add_f32_e32 v65, v83, v82
	v_add_f32_e32 v64, v67, v64
	v_sub_f32_e32 v66, v65, v83
	v_mul_f32_e32 v64, v81, v64
	v_sub_f32_e32 v66, v82, v66
	v_add_f32_e32 v66, v66, v64
	v_add_f32_e32 v68, v65, v66
	v_mul_f32_e32 v69, v68, v68
	v_fmamk_f32 v64, v69, 0x3e9b6dac, v110
	v_fmaak_f32 v99, v69, v64, 0x3f2aaada
	v_cvt_f32_i32_e32 v64, v76
	v_sub_f32_e32 v65, v68, v65
	v_sub_f32_e32 v65, v66, v65
	v_ldexp_f32 v70, v65, 1
	v_mul_f32_e32 v65, v68, v69
	v_ldexp_f32 v67, v68, 1
	v_pk_mul_f32 v[68:69], v[64:65], v[98:99]
	s_nop 0
	v_fma_f32 v66, v64, s59, -v68
	v_fmac_f32_e32 v66, 0xb102e308, v64
	v_pk_add_f32 v[64:65], v[68:69], v[66:67]
	s_nop 0
	v_sub_f32_e32 v67, v65, v67
	v_sub_f32_e32 v67, v69, v67
	v_add_f32_e32 v71, v70, v67
	v_mov_b32_e32 v70, v68
	v_pk_add_f32 v[68:69], v[64:65], v[68:69] neg_lo:[0,1] neg_hi:[0,1]
	v_pk_add_f32 v[76:77], v[64:65], v[70:71]
	v_mov_b32_e32 v67, v64
	v_mov_b32_e32 v69, v77
	v_pk_add_f32 v[80:81], v[66:67], v[68:69] neg_lo:[0,1] neg_hi:[0,1]
	v_pk_add_f32 v[66:67], v[66:67], v[68:69]
	v_mov_b32_e32 v70, v71
	v_pk_add_f32 v[68:69], v[66:67], v[64:65] op_sel:[1,0] op_sel_hi:[0,1] neg_lo:[0,1] neg_hi:[0,1]
	v_pk_add_f32 v[82:83], v[76:77], v[68:69] op_sel_hi:[1,0] neg_lo:[0,1] neg_hi:[0,1]
	v_mov_b32_e32 v76, v77
	v_mov_b32_e32 v77, v67
	v_pk_mov_b32 v[68:69], v[64:65], v[68:69] op_sel:[1,0]
	v_mov_b32_e32 v71, v64
	v_pk_add_f32 v[68:69], v[76:77], v[68:69] neg_lo:[0,1] neg_hi:[0,1]
	v_mov_b32_e32 v82, v80
	v_pk_add_f32 v[64:65], v[70:71], v[68:69] neg_lo:[0,1] neg_hi:[0,1]
	v_mov_b32_e32 v81, v67
	v_pk_add_f32 v[68:69], v[82:83], v[64:65]
	s_nop 0
	v_pk_add_f32 v[70:71], v[68:69], v[68:69] op_sel:[0,1] op_sel_hi:[1,0]
	s_nop 0
	v_pk_add_f32 v[66:67], v[66:67], v[70:71] op_sel:[1,0] op_sel_hi:[0,1]
	v_mov_b32_e32 v69, v66
	v_pk_add_f32 v[76:77], v[68:69], v[80:81] neg_lo:[0,1] neg_hi:[0,1]
	v_mov_b32_e32 v65, v70
	v_sub_f32_e32 v67, v68, v76
	v_pk_add_f32 v[64:65], v[64:65], v[76:77] neg_lo:[0,1] neg_hi:[0,1]
	v_sub_f32_e32 v67, v80, v67
	v_add_f32_e32 v64, v64, v67
	v_add_f32_e32 v64, v64, v65
	v_add_f32_e32 v64, v66, v64
	v_cndmask_b32_e32 v64, v114, v64, vcc
	v_cmp_ngt_f32_e32 vcc, -1.0, v84
	s_nop 1
	v_cndmask_b32_e32 v64, v115, v64, vcc
	v_cmp_neq_f32_e32 vcc, -1.0, v84
	s_nop 1
	v_cndmask_b32_e32 v64, v116, v64, vcc
	v_cmp_lt_f32_e64 vcc, |v84|, s61
	s_nop 1
	v_cndmask_b32_e32 v64, v64, v84, vcc

; __device__ __forceinline__ void phase1(const Params& p, unsigned char* smem) {
;     ...
;             else { float z = v[h] + p.dt_bias[h]; float sp = z > 20.f ? z : log1pf(__expf(z)); GG[o] = -__expf(p.a_log[h]) * sp; }
.LBB0_162:
	s_or_saveexec_b64 s[40:41], s[40:41]
	v_mov_b64_e32 v[76:77], 0xee1d000
	s_xor_b64 exec, exec, s[40:41]
	s_cbranch_execz .LBB0_166
	v_mov_b32_e32 v75, s76
	s_waitcnt lgkmcnt(1)
	v_add_f32_e32 v68, v68, v75
	v_cmp_nlt_f32_e32 vcc, s57, v68
	s_and_saveexec_b64 s[42:43], vcc
	s_cbranch_execz .LBB0_165
	v_mul_f32_e32 v68, 0x3fb8aa3b, v68
	v_exp_f32_e32 v68, v68
	s_nop 0
	v_add_f32_e32 v75, 1.0, v68
	v_frexp_mant_f32_e32 v79, v75
	v_cvt_f64_f32_e32 v[76:77], v75
	v_add_f32_e32 v78, -1.0, v75
	v_frexp_exp_i32_f64_e32 v76, v[76:77]
	v_cmp_gt_f32_e32 vcc, s58, v79
	v_sub_f32_e32 v80, v78, v75
	v_sub_f32_e32 v78, v68, v78
	v_subbrev_co_u32_e32 v84, vcc, 0, v76, vcc
	v_add_f32_e32 v80, 1.0, v80
	v_sub_u32_e32 v76, 0, v84
	v_add_f32_e32 v78, v78, v80
	v_ldexp_f32 v75, v75, v76
	v_ldexp_f32 v76, v78, v76
	v_add_f32_e32 v78, -1.0, v75
	v_add_f32_e32 v77, 1.0, v78
	v_sub_f32_e32 v77, v75, v77
	v_add_f32_e32 v79, v76, v77
	v_add_f32_e32 v77, 1.0, v75
	v_add_f32_e32 v80, -1.0, v77
	v_sub_f32_e32 v75, v75, v80
	v_add_f32_e32 v75, v76, v75
	v_add_f32_e32 v85, v77, v75
	v_rcp_f32_e32 v86, v85
	v_sub_f32_e32 v76, v85, v77
	v_add_f32_e32 v77, v78, v79
	v_sub_f32_e32 v75, v75, v76
	v_mul_f32_e32 v88, v77, v86
	v_sub_f32_e32 v76, v77, v78
	v_mul_f32_e32 v78, v85, v88
	v_fma_f32 v80, v88, v85, -v78
	v_fmac_f32_e32 v80, v88, v75
	v_sub_f32_e32 v87, v79, v76
	v_add_f32_e32 v76, v78, v80
	v_sub_f32_e32 v79, v77, v76
	v_pk_add_f32 v[82:83], v[76:77], v[78:79] neg_lo:[0,1] neg_hi:[0,1]
	v_mov_b32_e32 v81, v76
	v_pk_add_f32 v[76:77], v[82:83], v[80:81] neg_lo:[0,1] neg_hi:[0,1]
	v_cmp_neq_f32_e32 vcc, s60, v68
	v_add_f32_e32 v77, v87, v77
	v_add_f32_e32 v76, v76, v77
	v_add_f32_e32 v77, v79, v76
	v_mul_f32_e32 v87, v86, v77
	v_mul_f32_e32 v78, v85, v87
	v_fma_f32 v80, v87, v85, -v78
	v_fmac_f32_e32 v80, v87, v75
	v_sub_f32_e32 v75, v79, v77
	v_add_f32_e32 v75, v76, v75
	v_add_f32_e32 v76, v78, v80
	v_sub_f32_e32 v79, v77, v76
	v_pk_add_f32 v[82:83], v[76:77], v[78:79] neg_lo:[0,1] neg_hi:[0,1]
	v_mov_b32_e32 v81, v76
	v_pk_add_f32 v[76:77], v[82:83], v[80:81] neg_lo:[0,1] neg_hi:[0,1]
	s_nop 0
	v_add_f32_e32 v75, v75, v77
	v_add_f32_e32 v75, v76, v75
	v_add_f32_e32 v77, v88, v87
	v_add_f32_e32 v75, v79, v75
	v_sub_f32_e32 v76, v77, v88
	v_mul_f32_e32 v75, v86, v75
	v_sub_f32_e32 v76, v87, v76
	v_add_f32_e32 v75, v76, v75
	v_add_f32_e32 v78, v77, v75
	v_mul_f32_e32 v80, v78, v78
	v_fmamk_f32 v76, v80, 0x3e9b6dac, v110
	v_fmaak_f32 v99, v80, v76, 0x3f2aaada
	v_cvt_f32_i32_e32 v76, v84
	v_sub_f32_e32 v77, v78, v77
	v_sub_f32_e32 v75, v75, v77
	v_mul_f32_e32 v77, v78, v80
	v_pk_mul_f32 v[80:81], v[76:77], v[98:99]
	v_ldexp_f32 v79, v78, 1
	v_fma_f32 v78, v76, s59, -v80
	v_fmac_f32_e32 v78, 0xb102e308, v76
	v_pk_add_f32 v[76:77], v[80:81], v[78:79]
	v_ldexp_f32 v75, v75, 1
	v_sub_f32_e32 v79, v77, v79
	v_sub_f32_e32 v79, v81, v79
	v_add_f32_e32 v83, v75, v79
	v_mov_b32_e32 v82, v80
	v_pk_add_f32 v[80:81], v[76:77], v[80:81] neg_lo:[0,1] neg_hi:[0,1]
	v_pk_add_f32 v[84:85], v[76:77], v[82:83]
	v_mov_b32_e32 v79, v76
	v_mov_b32_e32 v81, v85
	v_pk_add_f32 v[86:87], v[78:79], v[80:81] neg_lo:[0,1] neg_hi:[0,1]
	v_pk_add_f32 v[78:79], v[78:79], v[80:81]
	v_mov_b32_e32 v82, v83
	v_pk_add_f32 v[80:81], v[78:79], v[76:77] op_sel:[1,0] op_sel_hi:[0,1] neg_lo:[0,1] neg_hi:[0,1]
	v_pk_add_f32 v[88:89], v[84:85], v[80:81] op_sel_hi:[1,0] neg_lo:[0,1] neg_hi:[0,1]
	v_mov_b32_e32 v84, v85
	v_mov_b32_e32 v85, v79
	v_pk_mov_b32 v[80:81], v[76:77], v[80:81] op_sel:[1,0]
	v_mov_b32_e32 v83, v76
	v_pk_add_f32 v[80:81], v[84:85], v[80:81] neg_lo:[0,1] neg_hi:[0,1]
	v_mov_b32_e32 v88, v86
	v_pk_add_f32 v[76:77], v[82:83], v[80:81] neg_lo:[0,1] neg_hi:[0,1]
	v_mov_b32_e32 v87, v79
	v_pk_add_f32 v[80:81], v[88:89], v[76:77]
	s_nop 0
	v_pk_add_f32 v[82:83], v[80:81], v[80:81] op_sel:[0,1] op_sel_hi:[1,0]
	s_nop 0
	v_pk_add_f32 v[78:79], v[78:79], v[82:83] op_sel:[1,0] op_sel_hi:[0,1]
	v_mov_b32_e32 v81, v78
	v_pk_add_f32 v[84:85], v[80:81], v[86:87] neg_lo:[0,1] neg_hi:[0,1]
	v_mov_b32_e32 v77, v82
	v_sub_f32_e32 v75, v80, v84
	v_pk_add_f32 v[76:77], v[76:77], v[84:85] neg_lo:[0,1] neg_hi:[0,1]
	v_sub_f32_e32 v75, v86, v75
	v_add_f32_e32 v75, v76, v75
	v_add_f32_e32 v75, v75, v77
	v_add_f32_e32 v75, v78, v75
	v_cndmask_b32_e32 v75, v114, v75, vcc
	v_cmp_ngt_f32_e32 vcc, -1.0, v68
	s_nop 1
	v_cndmask_b32_e32 v75, v115, v75, vcc
	v_cmp_neq_f32_e32 vcc, -1.0, v68
	s_nop 1
	v_cndmask_b32_e32 v75, v116, v75, vcc
	v_cmp_lt_f32_e64 vcc, |v68|, s61
	s_nop 1
	v_cndmask_b32_e32 v68, v75, v68, vcc
.LBB0_165:
	s_or_b64 exec, exec, s[42:43]
	v_mov_b32_e32 v75, s92
	v_mov_b64_e32 v[76:77], 0xee9e000
	s_nop 0
	v_mul_f32_e32 v75, 0x3fb8aa3b, v75
	v_exp_f32_e32 v75, v75
	s_nop 0
	v_mul_f32_e64 v79, v68, -v75

; __device__ __forceinline__ float sigmoidf_(float x) { return 1.f / (1.f + __expf(-x)); }
; __device__ __forceinline__ void phase1(const Params& p, unsigned char* smem) {
;     ...
;           for (int h = 0; h < 8; ++h) {
;             size_t o = (size_t)(bb * 8 + h) * LPAD + pos + 48;
;             if (!isg) BETA[o] = sigmoidf_(v[h]);
;             else { float z = v[h] + p.dt_bias[h]; float sp = z > 20.f ? z : log1pf(__expf(z)); GG[o] = -__expf(p.a_log[h]) * sp; }
.LBB0_168:
	s_or_saveexec_b64 s[40:41], s[40:41]
	v_mov_b64_e32 v[76:77], 0xee1d000
	s_xor_b64 exec, exec, s[40:41]
	s_cbranch_execz .LBB0_172
	v_mov_b32_e32 v68, s77
	s_nop 0
	v_add_f32_e32 v68, v69, v68
	v_cmp_nlt_f32_e32 vcc, s57, v68
	s_and_saveexec_b64 s[42:43], vcc
	s_cbranch_execz .LBB0_171
	v_mul_f32_e32 v68, 0x3fb8aa3b, v68
	v_exp_f32_e32 v79, v68
	s_nop 0
	v_add_f32_e32 v76, 1.0, v79
	v_frexp_mant_f32_e32 v80, v76
	v_cvt_f64_f32_e32 v[68:69], v76
	v_frexp_exp_i32_f64_e32 v68, v[68:69]
	v_cmp_gt_f32_e32 vcc, s58, v80
	v_add_f32_e32 v77, -1.0, v76
	v_sub_f32_e32 v81, v77, v76
	v_subbrev_co_u32_e32 v84, vcc, 0, v68, vcc
	v_sub_u32_e32 v68, 0, v84
	v_sub_f32_e32 v77, v79, v77
	v_add_f32_e32 v81, 1.0, v81
	v_ldexp_f32 v69, v76, v68
	v_add_f32_e32 v77, v77, v81
	v_add_f32_e32 v76, -1.0, v69
	v_add_f32_e32 v80, 1.0, v69
	v_ldexp_f32 v68, v77, v68
	v_add_f32_e32 v77, 1.0, v76
	v_add_f32_e32 v81, -1.0, v80
	v_sub_f32_e32 v77, v69, v77
	v_sub_f32_e32 v69, v69, v81
	v_add_f32_e32 v77, v68, v77
	v_add_f32_e32 v68, v68, v69
	v_add_f32_e32 v85, v80, v68
	v_rcp_f32_e32 v87, v85
	v_sub_f32_e32 v69, v85, v80
	v_sub_f32_e32 v86, v68, v69
	v_add_f32_e32 v69, v76, v77
	v_mul_f32_e32 v89, v69, v87
	v_sub_f32_e32 v68, v69, v76
	v_mul_f32_e32 v76, v85, v89
	v_fma_f32 v80, v89, v85, -v76
	v_fmac_f32_e32 v80, v89, v86
	v_sub_f32_e32 v88, v77, v68
	v_add_f32_e32 v68, v76, v80
	v_sub_f32_e32 v77, v69, v68
	v_pk_add_f32 v[82:83], v[68:69], v[76:77] neg_lo:[0,1] neg_hi:[0,1]
	v_mov_b32_e32 v81, v68
	v_pk_add_f32 v[68:69], v[82:83], v[80:81] neg_lo:[0,1] neg_hi:[0,1]
	v_cmp_neq_f32_e32 vcc, s60, v79
	v_add_f32_e32 v69, v88, v69
	v_add_f32_e32 v68, v68, v69
	v_add_f32_e32 v69, v77, v68
	v_mul_f32_e32 v88, v87, v69
	v_mul_f32_e32 v76, v85, v88
	v_fma_f32 v80, v88, v85, -v76
	v_fmac_f32_e32 v80, v88, v86
	v_sub_f32_e32 v77, v77, v69
	v_add_f32_e32 v85, v68, v77
	v_add_f32_e32 v68, v76, v80
	v_sub_f32_e32 v77, v69, v68
	v_pk_add_f32 v[82:83], v[68:69], v[76:77] neg_lo:[0,1] neg_hi:[0,1]
	v_mov_b32_e32 v81, v68
	v_pk_add_f32 v[68:69], v[82:83], v[80:81] neg_lo:[0,1] neg_hi:[0,1]
	s_nop 0
	v_add_f32_e32 v69, v85, v69
	v_add_f32_e32 v68, v68, v69
	v_add_f32_e32 v69, v89, v88
	v_add_f32_e32 v68, v77, v68
	v_sub_f32_e32 v76, v69, v89
	v_mul_f32_e32 v68, v87, v68
	v_sub_f32_e32 v76, v88, v76
	v_add_f32_e32 v76, v76, v68
	v_add_f32_e32 v80, v69, v76
	v_mul_f32_e32 v81, v80, v80
	v_fmamk_f32 v68, v81, 0x3e9b6dac, v110
	v_fmaak_f32 v99, v81, v68, 0x3f2aaada
	v_cvt_f32_i32_e32 v68, v84
	v_sub_f32_e32 v69, v80, v69
	v_sub_f32_e32 v69, v76, v69
	v_ldexp_f32 v82, v69, 1
	v_mul_f32_e32 v69, v80, v81
	v_ldexp_f32 v77, v80, 1
	v_pk_mul_f32 v[80:81], v[68:69], v[98:99]
	s_nop 0
	v_fma_f32 v76, v68, s59, -v80
	v_fmac_f32_e32 v76, 0xb102e308, v68
	v_pk_add_f32 v[68:69], v[80:81], v[76:77]
	s_nop 0
	v_sub_f32_e32 v77, v69, v77
	v_sub_f32_e32 v77, v81, v77
	v_add_f32_e32 v83, v82, v77
	v_mov_b32_e32 v82, v80
	v_pk_add_f32 v[80:81], v[68:69], v[80:81] neg_lo:[0,1] neg_hi:[0,1]
	v_pk_add_f32 v[84:85], v[68:69], v[82:83]
	v_mov_b32_e32 v77, v68
	v_mov_b32_e32 v81, v85
	v_pk_add_f32 v[86:87], v[76:77], v[80:81] neg_lo:[0,1] neg_hi:[0,1]
	v_pk_add_f32 v[76:77], v[76:77], v[80:81]
	v_mov_b32_e32 v82, v83
	v_pk_add_f32 v[80:81], v[76:77], v[68:69] op_sel:[1,0] op_sel_hi:[0,1] neg_lo:[0,1] neg_hi:[0,1]
	v_pk_add_f32 v[88:89], v[84:85], v[80:81] op_sel_hi:[1,0] neg_lo:[0,1] neg_hi:[0,1]
	v_mov_b32_e32 v84, v85
	v_mov_b32_e32 v85, v77
	v_pk_mov_b32 v[80:81], v[68:69], v[80:81] op_sel:[1,0]
	v_mov_b32_e32 v83, v68
	v_pk_add_f32 v[80:81], v[84:85], v[80:81] neg_lo:[0,1] neg_hi:[0,1]
	v_mov_b32_e32 v88, v86
	v_pk_add_f32 v[68:69], v[82:83], v[80:81] neg_lo:[0,1] neg_hi:[0,1]
	v_mov_b32_e32 v87, v77
	v_pk_add_f32 v[80:81], v[88:89], v[68:69]
	s_nop 0
	v_pk_add_f32 v[82:83], v[80:81], v[80:81] op_sel:[0,1] op_sel_hi:[1,0]
	s_nop 0
	v_pk_add_f32 v[76:77], v[76:77], v[82:83] op_sel:[1,0] op_sel_hi:[0,1]
	v_mov_b32_e32 v81, v76
	v_pk_add_f32 v[84:85], v[80:81], v[86:87] neg_lo:[0,1] neg_hi:[0,1]
	v_mov_b32_e32 v69, v82
	v_sub_f32_e32 v77, v80, v84
	v_pk_add_f32 v[68:69], v[68:69], v[84:85] neg_lo:[0,1] neg_hi:[0,1]
	v_sub_f32_e32 v77, v86, v77
	v_add_f32_e32 v68, v68, v77
	v_add_f32_e32 v68, v68, v69
	v_add_f32_e32 v68, v76, v68
	v_cndmask_b32_e32 v68, v114, v68, vcc
	v_cmp_ngt_f32_e32 vcc, -1.0, v79
	s_nop 1
	v_cndmask_b32_e32 v68, v115, v68, vcc
	v_cmp_neq_f32_e32 vcc, -1.0, v79
	s_nop 1
	v_cndmask_b32_e32 v68, v116, v68, vcc
	v_cmp_lt_f32_e64 vcc, |v79|, s61
	s_nop 1
	v_cndmask_b32_e32 v68, v68, v79, vcc

; __device__ __forceinline__ float sigmoidf_(float x) { return 1.f / (1.f + __expf(-x)); }
; __device__ __forceinline__ void phase1(const Params& p, unsigned char* smem) {
;     ...
;           for (int h = 0; h < 8; ++h) {
;             size_t o = (size_t)(bb * 8 + h) * LPAD + pos + 48;
;             if (!isg) BETA[o] = sigmoidf_(v[h]);
;             else { float z = v[h] + p.dt_bias[h]; float sp = z > 20.f ? z : log1pf(__expf(z)); GG[o] = -__expf(p.a_log[h]) * sp; }
.LBB0_174:
	s_or_saveexec_b64 s[40:41], s[40:41]
	v_mov_b64_e32 v[68:69], 0xee1d000
	s_xor_b64 exec, exec, s[40:41]
	s_cbranch_execz .LBB0_178
	v_mov_b32_e32 v68, s78
	s_nop 0
	v_add_f32_e32 v68, v70, v68
	v_cmp_nlt_f32_e32 vcc, s57, v68
	s_and_saveexec_b64 s[42:43], vcc
	s_cbranch_execz .LBB0_177
	v_mul_f32_e32 v68, 0x3fb8aa3b, v68
	v_exp_f32_e32 v70, v68
	s_nop 0
	v_add_f32_e32 v76, 1.0, v70
	v_frexp_mant_f32_e32 v79, v76
	v_cvt_f64_f32_e32 v[68:69], v76
	v_frexp_exp_i32_f64_e32 v68, v[68:69]
	v_cmp_gt_f32_e32 vcc, s58, v79
	v_add_f32_e32 v77, -1.0, v76
	v_sub_f32_e32 v80, v77, v76
	v_subbrev_co_u32_e32 v79, vcc, 0, v68, vcc
	v_sub_u32_e32 v68, 0, v79
	v_sub_f32_e32 v77, v70, v77
	v_add_f32_e32 v80, 1.0, v80
	v_ldexp_f32 v69, v76, v68
	v_add_f32_e32 v77, v77, v80
	v_add_f32_e32 v76, -1.0, v69
	v_add_f32_e32 v80, 1.0, v69
	v_ldexp_f32 v68, v77, v68
	v_add_f32_e32 v77, 1.0, v76
	v_add_f32_e32 v81, -1.0, v80
	v_sub_f32_e32 v77, v69, v77
	v_sub_f32_e32 v69, v69, v81
	v_add_f32_e32 v77, v68, v77
	v_add_f32_e32 v68, v68, v69
	v_add_f32_e32 v84, v80, v68
	v_rcp_f32_e32 v86, v84
	v_sub_f32_e32 v69, v84, v80
	v_sub_f32_e32 v85, v68, v69
	v_add_f32_e32 v69, v76, v77
	v_mul_f32_e32 v88, v69, v86
	v_sub_f32_e32 v68, v69, v76
	v_mul_f32_e32 v76, v84, v88
	v_fma_f32 v80, v88, v84, -v76
	v_fmac_f32_e32 v80, v88, v85
	v_sub_f32_e32 v87, v77, v68
	v_add_f32_e32 v68, v76, v80
	v_sub_f32_e32 v77, v69, v68
	v_pk_add_f32 v[82:83], v[68:69], v[76:77] neg_lo:[0,1] neg_hi:[0,1]
	v_mov_b32_e32 v81, v68
	v_pk_add_f32 v[68:69], v[82:83], v[80:81] neg_lo:[0,1] neg_hi:[0,1]
	v_cmp_neq_f32_e32 vcc, s60, v70
	v_add_f32_e32 v69, v87, v69
	v_add_f32_e32 v68, v68, v69
	v_add_f32_e32 v69, v77, v68
	v_mul_f32_e32 v87, v86, v69
	v_mul_f32_e32 v76, v84, v87
	v_fma_f32 v80, v87, v84, -v76
	v_fmac_f32_e32 v80, v87, v85
	v_sub_f32_e32 v77, v77, v69
	v_add_f32_e32 v84, v68, v77
	v_add_f32_e32 v68, v76, v80
	v_sub_f32_e32 v77, v69, v68
	v_pk_add_f32 v[82:83], v[68:69], v[76:77] neg_lo:[0,1] neg_hi:[0,1]
	v_mov_b32_e32 v81, v68
	v_pk_add_f32 v[68:69], v[82:83], v[80:81] neg_lo:[0,1] neg_hi:[0,1]
	s_nop 0
	v_add_f32_e32 v69, v84, v69
	v_add_f32_e32 v68, v68, v69
	v_add_f32_e32 v69, v88, v87
	v_add_f32_e32 v68, v77, v68
	v_sub_f32_e32 v76, v69, v88
	v_mul_f32_e32 v68, v86, v68
	v_sub_f32_e32 v76, v87, v76
	v_add_f32_e32 v76, v76, v68
	v_add_f32_e32 v80, v69, v76
	v_mul_f32_e32 v81, v80, v80
	v_fmamk_f32 v68, v81, 0x3e9b6dac, v110
	v_fmaak_f32 v99, v81, v68, 0x3f2aaada
	v_cvt_f32_i32_e32 v68, v79
	v_sub_f32_e32 v69, v80, v69
	v_sub_f32_e32 v69, v76, v69
	v_ldexp_f32 v79, v69, 1
	v_mul_f32_e32 v69, v80, v81
	v_ldexp_f32 v77, v80, 1
	v_pk_mul_f32 v[80:81], v[68:69], v[98:99]
	s_nop 0
	v_fma_f32 v76, v68, s59, -v80
	v_fmac_f32_e32 v76, 0xb102e308, v68
	v_pk_add_f32 v[68:69], v[80:81], v[76:77]
	v_mov_b32_e32 v82, v80
	v_sub_f32_e32 v77, v69, v77
	v_sub_f32_e32 v77, v81, v77
	v_add_f32_e32 v83, v79, v77
	v_pk_add_f32 v[80:81], v[68:69], v[80:81] neg_lo:[0,1] neg_hi:[0,1]
	v_pk_add_f32 v[84:85], v[68:69], v[82:83]
	v_mov_b32_e32 v77, v68
	v_mov_b32_e32 v81, v85
	v_pk_add_f32 v[86:87], v[76:77], v[80:81] neg_lo:[0,1] neg_hi:[0,1]
	v_pk_add_f32 v[76:77], v[76:77], v[80:81]
	v_mov_b32_e32 v82, v83
	v_pk_add_f32 v[80:81], v[76:77], v[68:69] op_sel:[1,0] op_sel_hi:[0,1] neg_lo:[0,1] neg_hi:[0,1]
	v_pk_add_f32 v[88:89], v[84:85], v[80:81] op_sel_hi:[1,0] neg_lo:[0,1] neg_hi:[0,1]
	v_mov_b32_e32 v84, v85
	v_mov_b32_e32 v85, v77
	v_pk_mov_b32 v[80:81], v[68:69], v[80:81] op_sel:[1,0]
	v_mov_b32_e32 v83, v68
	v_pk_add_f32 v[80:81], v[84:85], v[80:81] neg_lo:[0,1] neg_hi:[0,1]
	v_mov_b32_e32 v88, v86
	v_pk_add_f32 v[68:69], v[82:83], v[80:81] neg_lo:[0,1] neg_hi:[0,1]
	v_mov_b32_e32 v87, v77
	v_pk_add_f32 v[80:81], v[88:89], v[68:69]
	s_nop 0
	v_pk_add_f32 v[82:83], v[80:81], v[80:81] op_sel:[0,1] op_sel_hi:[1,0]
	s_nop 0
	v_pk_add_f32 v[76:77], v[76:77], v[82:83] op_sel:[1,0] op_sel_hi:[0,1]
	v_mov_b32_e32 v81, v76
	v_pk_add_f32 v[84:85], v[80:81], v[86:87] neg_lo:[0,1] neg_hi:[0,1]
	v_mov_b32_e32 v69, v82
	v_sub_f32_e32 v77, v80, v84
	v_pk_add_f32 v[68:69], v[68:69], v[84:85] neg_lo:[0,1] neg_hi:[0,1]
	v_sub_f32_e32 v77, v86, v77
	v_add_f32_e32 v68, v68, v77
	v_add_f32_e32 v68, v68, v69
	v_add_f32_e32 v68, v76, v68
	v_cndmask_b32_e32 v68, v114, v68, vcc
	v_cmp_ngt_f32_e32 vcc, -1.0, v70
	s_nop 1
	v_cndmask_b32_e32 v68, v115, v68, vcc
	v_cmp_neq_f32_e32 vcc, -1.0, v70
	s_nop 1
	v_cndmask_b32_e32 v68, v116, v68, vcc
	v_cmp_lt_f32_e64 vcc, |v70|, s61
	s_nop 1
	v_cndmask_b32_e32 v68, v68, v70, vcc

; __device__ __forceinline__ float sigmoidf_(float x) { return 1.f / (1.f + __expf(-x)); }
; __device__ __forceinline__ void phase1(const Params& p, unsigned char* smem) {
;     ...
;           for (int h = 0; h < 8; ++h) {
;             size_t o = (size_t)(bb * 8 + h) * LPAD + pos + 48;
;             if (!isg) BETA[o] = sigmoidf_(v[h]);
;             else { float z = v[h] + p.dt_bias[h]; float sp = z > 20.f ? z : log1pf(__expf(z)); GG[o] = -__expf(p.a_log[h]) * sp; }
.LBB0_180:
	s_or_saveexec_b64 s[40:41], s[40:41]
	v_mov_b64_e32 v[68:69], 0xee1d000
	s_xor_b64 exec, exec, s[40:41]
	s_cbranch_execz .LBB0_184
	v_mov_b32_e32 v68, s79
	s_nop 0
	v_add_f32_e32 v68, v71, v68
	v_cmp_nlt_f32_e32 vcc, s57, v68
	s_and_saveexec_b64 s[42:43], vcc
	s_cbranch_execz .LBB0_183
	v_mul_f32_e32 v68, 0x3fb8aa3b, v68
	v_exp_f32_e32 v79, v68
	s_nop 0
	v_add_f32_e32 v70, 1.0, v79
	v_frexp_mant_f32_e32 v76, v70
	v_cvt_f64_f32_e32 v[68:69], v70
	v_frexp_exp_i32_f64_e32 v68, v[68:69]
	v_cmp_gt_f32_e32 vcc, s58, v76
	v_add_f32_e32 v71, -1.0, v70
	v_sub_f32_e32 v77, v71, v70
	v_subbrev_co_u32_e32 v82, vcc, 0, v68, vcc
	v_sub_u32_e32 v68, 0, v82
	v_sub_f32_e32 v71, v79, v71
	v_add_f32_e32 v77, 1.0, v77
	v_ldexp_f32 v69, v70, v68
	v_add_f32_e32 v71, v71, v77
	v_add_f32_e32 v70, -1.0, v69
	v_add_f32_e32 v76, 1.0, v69
	v_ldexp_f32 v68, v71, v68
	v_add_f32_e32 v71, 1.0, v70
	v_add_f32_e32 v77, -1.0, v76
	v_sub_f32_e32 v71, v69, v71
	v_sub_f32_e32 v69, v69, v77
	v_add_f32_e32 v71, v68, v71
	v_add_f32_e32 v68, v68, v69
	v_add_f32_e32 v83, v76, v68
	v_rcp_f32_e32 v85, v83
	v_sub_f32_e32 v69, v83, v76
	v_sub_f32_e32 v84, v68, v69
	v_add_f32_e32 v69, v70, v71
	v_mul_f32_e32 v87, v69, v85
	v_sub_f32_e32 v68, v69, v70
	v_mul_f32_e32 v70, v83, v87
	v_fma_f32 v76, v87, v83, -v70
	v_fmac_f32_e32 v76, v87, v84
	v_sub_f32_e32 v86, v71, v68
	v_add_f32_e32 v68, v70, v76
	v_sub_f32_e32 v71, v69, v68
	v_pk_add_f32 v[80:81], v[68:69], v[70:71] neg_lo:[0,1] neg_hi:[0,1]
	v_mov_b32_e32 v77, v68
	v_pk_add_f32 v[68:69], v[80:81], v[76:77] neg_lo:[0,1] neg_hi:[0,1]
	v_cmp_neq_f32_e32 vcc, s60, v79
	v_add_f32_e32 v69, v86, v69
	v_add_f32_e32 v68, v68, v69
	v_add_f32_e32 v69, v71, v68
	v_mul_f32_e32 v86, v85, v69
	v_mul_f32_e32 v70, v83, v86
	v_fma_f32 v76, v86, v83, -v70
	v_fmac_f32_e32 v76, v86, v84
	v_sub_f32_e32 v71, v71, v69
	v_add_f32_e32 v83, v68, v71
	v_add_f32_e32 v68, v70, v76
	v_sub_f32_e32 v71, v69, v68
	v_pk_add_f32 v[80:81], v[68:69], v[70:71] neg_lo:[0,1] neg_hi:[0,1]
	v_mov_b32_e32 v77, v68
	v_pk_add_f32 v[68:69], v[80:81], v[76:77] neg_lo:[0,1] neg_hi:[0,1]
	s_nop 0
	v_add_f32_e32 v69, v83, v69
	v_add_f32_e32 v68, v68, v69
	v_add_f32_e32 v69, v87, v86
	v_add_f32_e32 v68, v71, v68
	v_sub_f32_e32 v70, v69, v87
	v_mul_f32_e32 v68, v85, v68
	v_sub_f32_e32 v70, v86, v70
	v_add_f32_e32 v70, v70, v68
	v_add_f32_e32 v76, v69, v70
	v_mul_f32_e32 v77, v76, v76
	v_fmamk_f32 v68, v77, 0x3e9b6dac, v110
	v_fmaak_f32 v99, v77, v68, 0x3f2aaada
	v_cvt_f32_i32_e32 v68, v82
	v_sub_f32_e32 v69, v76, v69
	v_sub_f32_e32 v69, v70, v69
	v_ldexp_f32 v80, v69, 1
	v_mul_f32_e32 v69, v76, v77
	v_ldexp_f32 v71, v76, 1
	v_pk_mul_f32 v[76:77], v[68:69], v[98:99]
	s_nop 0
	v_fma_f32 v70, v68, s59, -v76
	v_fmac_f32_e32 v70, 0xb102e308, v68
	v_pk_add_f32 v[68:69], v[76:77], v[70:71]
	s_nop 0
	v_sub_f32_e32 v71, v69, v71
	v_sub_f32_e32 v71, v77, v71
	v_add_f32_e32 v81, v80, v71
	v_mov_b32_e32 v80, v76
	v_pk_add_f32 v[76:77], v[68:69], v[76:77] neg_lo:[0,1] neg_hi:[0,1]
	v_pk_add_f32 v[82:83], v[68:69], v[80:81]
	v_mov_b32_e32 v71, v68
	v_mov_b32_e32 v77, v83
	v_pk_add_f32 v[84:85], v[70:71], v[76:77] neg_lo:[0,1] neg_hi:[0,1]
	v_pk_add_f32 v[70:71], v[70:71], v[76:77]
	v_mov_b32_e32 v80, v81
	v_pk_add_f32 v[76:77], v[70:71], v[68:69] op_sel:[1,0] op_sel_hi:[0,1] neg_lo:[0,1] neg_hi:[0,1]
	v_pk_add_f32 v[86:87], v[82:83], v[76:77] op_sel_hi:[1,0] neg_lo:[0,1] neg_hi:[0,1]
	v_mov_b32_e32 v82, v83
	v_mov_b32_e32 v83, v71
	v_pk_mov_b32 v[76:77], v[68:69], v[76:77] op_sel:[1,0]
	v_mov_b32_e32 v81, v68
	v_pk_add_f32 v[76:77], v[82:83], v[76:77] neg_lo:[0,1] neg_hi:[0,1]
	v_mov_b32_e32 v86, v84
	v_pk_add_f32 v[68:69], v[80:81], v[76:77] neg_lo:[0,1] neg_hi:[0,1]
	v_mov_b32_e32 v85, v71
	v_pk_add_f32 v[76:77], v[86:87], v[68:69]
	s_nop 0
	v_pk_add_f32 v[80:81], v[76:77], v[76:77] op_sel:[0,1] op_sel_hi:[1,0]
	s_nop 0
	v_pk_add_f32 v[70:71], v[70:71], v[80:81] op_sel:[1,0] op_sel_hi:[0,1]
	v_mov_b32_e32 v77, v70
	v_pk_add_f32 v[82:83], v[76:77], v[84:85] neg_lo:[0,1] neg_hi:[0,1]
	v_mov_b32_e32 v69, v80
	v_sub_f32_e32 v71, v76, v82
	v_pk_add_f32 v[68:69], v[68:69], v[82:83] neg_lo:[0,1] neg_hi:[0,1]
	v_sub_f32_e32 v71, v84, v71
	v_add_f32_e32 v68, v68, v71
	v_add_f32_e32 v68, v68, v69
	v_add_f32_e32 v68, v70, v68
	v_cndmask_b32_e32 v68, v114, v68, vcc
	v_cmp_ngt_f32_e32 vcc, -1.0, v79
	s_nop 1
	v_cndmask_b32_e32 v68, v115, v68, vcc
	v_cmp_neq_f32_e32 vcc, -1.0, v79
	s_nop 1
	v_cndmask_b32_e32 v68, v116, v68, vcc
	v_cmp_lt_f32_e64 vcc, |v79|, s61
	s_nop 1
	v_cndmask_b32_e32 v68, v68, v79, vcc

; __device__ __forceinline__ float sigmoidf_(float x) { return 1.f / (1.f + __expf(-x)); }
; __device__ __forceinline__ void phase1(const Params& p, unsigned char* smem) {
;     ...
;           for (int h = 0; h < 8; ++h) {
;             size_t o = (size_t)(bb * 8 + h) * LPAD + pos + 48;
;             if (!isg) BETA[o] = sigmoidf_(v[h]);
;             else { float z = v[h] + p.dt_bias[h]; float sp = z > 20.f ? z : log1pf(__expf(z)); GG[o] = -__expf(p.a_log[h]) * sp; }
.LBB0_186:
	s_or_saveexec_b64 s[40:41], s[40:41]
	v_mov_b64_e32 v[68:69], 0xee1d000
	s_xor_b64 exec, exec, s[40:41]
	s_cbranch_execz .LBB0_190
	v_mov_b32_e32 v68, s80
	s_waitcnt lgkmcnt(0)
	v_add_f32_e32 v64, v64, v68
	v_cmp_nlt_f32_e32 vcc, s57, v64
	s_and_saveexec_b64 s[42:43], vcc
	s_cbranch_execz .LBB0_189
	v_mul_f32_e32 v64, 0x3fb8aa3b, v64
	v_exp_f32_e32 v64, v64
	s_nop 0
	v_add_f32_e32 v70, 1.0, v64
	v_frexp_mant_f32_e32 v76, v70
	v_cvt_f64_f32_e32 v[68:69], v70
	v_frexp_exp_i32_f64_e32 v68, v[68:69]
	v_cmp_gt_f32_e32 vcc, s58, v76
	v_add_f32_e32 v71, -1.0, v70
	v_sub_f32_e32 v77, v71, v70
	v_subbrev_co_u32_e32 v79, vcc, 0, v68, vcc
	v_sub_u32_e32 v68, 0, v79
	v_sub_f32_e32 v71, v64, v71
	v_add_f32_e32 v77, 1.0, v77
	v_ldexp_f32 v69, v70, v68
	v_add_f32_e32 v71, v71, v77
	v_add_f32_e32 v70, -1.0, v69
	v_add_f32_e32 v76, 1.0, v69
	v_ldexp_f32 v68, v71, v68
	v_add_f32_e32 v71, 1.0, v70
	v_add_f32_e32 v77, -1.0, v76
	v_sub_f32_e32 v71, v69, v71
	v_sub_f32_e32 v69, v69, v77
	v_add_f32_e32 v71, v68, v71
	v_add_f32_e32 v68, v68, v69
	v_add_f32_e32 v82, v76, v68
	v_rcp_f32_e32 v84, v82
	v_sub_f32_e32 v69, v82, v76
	v_sub_f32_e32 v83, v68, v69
	v_add_f32_e32 v69, v70, v71
	v_mul_f32_e32 v86, v69, v84
	v_sub_f32_e32 v68, v69, v70
	v_mul_f32_e32 v70, v82, v86
	v_fma_f32 v76, v86, v82, -v70
	v_fmac_f32_e32 v76, v86, v83
	v_sub_f32_e32 v85, v71, v68
	v_add_f32_e32 v68, v70, v76
	v_sub_f32_e32 v71, v69, v68
	v_pk_add_f32 v[80:81], v[68:69], v[70:71] neg_lo:[0,1] neg_hi:[0,1]
	v_mov_b32_e32 v77, v68
	v_pk_add_f32 v[68:69], v[80:81], v[76:77] neg_lo:[0,1] neg_hi:[0,1]
	v_cmp_neq_f32_e32 vcc, s60, v64
	v_add_f32_e32 v69, v85, v69
	v_add_f32_e32 v68, v68, v69
	v_add_f32_e32 v69, v71, v68
	v_mul_f32_e32 v85, v84, v69
	v_mul_f32_e32 v70, v82, v85
	v_fma_f32 v76, v85, v82, -v70
	v_fmac_f32_e32 v76, v85, v83
	v_sub_f32_e32 v71, v71, v69
	v_add_f32_e32 v82, v68, v71
	v_add_f32_e32 v68, v70, v76
	v_sub_f32_e32 v71, v69, v68
	v_pk_add_f32 v[80:81], v[68:69], v[70:71] neg_lo:[0,1] neg_hi:[0,1]
	v_mov_b32_e32 v77, v68
	v_pk_add_f32 v[68:69], v[80:81], v[76:77] neg_lo:[0,1] neg_hi:[0,1]
	s_nop 0
	v_add_f32_e32 v69, v82, v69
	v_add_f32_e32 v68, v68, v69
	v_add_f32_e32 v69, v86, v85
	v_add_f32_e32 v68, v71, v68
	v_sub_f32_e32 v70, v69, v86
	v_mul_f32_e32 v68, v84, v68
	v_sub_f32_e32 v70, v85, v70
	v_add_f32_e32 v70, v70, v68
	v_add_f32_e32 v76, v69, v70
	v_mul_f32_e32 v77, v76, v76
	v_fmamk_f32 v68, v77, 0x3e9b6dac, v110
	v_fmaak_f32 v99, v77, v68, 0x3f2aaada
	v_cvt_f32_i32_e32 v68, v79
	v_sub_f32_e32 v69, v76, v69
	v_sub_f32_e32 v69, v70, v69
	v_ldexp_f32 v79, v69, 1
	v_mul_f32_e32 v69, v76, v77
	v_ldexp_f32 v71, v76, 1
	v_pk_mul_f32 v[76:77], v[68:69], v[98:99]
	s_nop 0
	v_fma_f32 v70, v68, s59, -v76
	v_fmac_f32_e32 v70, 0xb102e308, v68
	v_pk_add_f32 v[68:69], v[76:77], v[70:71]
	v_mov_b32_e32 v80, v76
	v_sub_f32_e32 v71, v69, v71
	v_sub_f32_e32 v71, v77, v71
	v_add_f32_e32 v81, v79, v71
	v_pk_add_f32 v[76:77], v[68:69], v[76:77] neg_lo:[0,1] neg_hi:[0,1]
	v_pk_add_f32 v[82:83], v[68:69], v[80:81]
	v_mov_b32_e32 v71, v68
	v_mov_b32_e32 v77, v83
	v_pk_add_f32 v[84:85], v[70:71], v[76:77] neg_lo:[0,1] neg_hi:[0,1]
	v_pk_add_f32 v[70:71], v[70:71], v[76:77]
	v_mov_b32_e32 v80, v81
	v_pk_add_f32 v[76:77], v[70:71], v[68:69] op_sel:[1,0] op_sel_hi:[0,1] neg_lo:[0,1] neg_hi:[0,1]
	v_pk_add_f32 v[86:87], v[82:83], v[76:77] op_sel_hi:[1,0] neg_lo:[0,1] neg_hi:[0,1]
	v_mov_b32_e32 v82, v83
	v_mov_b32_e32 v83, v71
	v_pk_mov_b32 v[76:77], v[68:69], v[76:77] op_sel:[1,0]
	v_mov_b32_e32 v81, v68
	v_pk_add_f32 v[76:77], v[82:83], v[76:77] neg_lo:[0,1] neg_hi:[0,1]
	v_mov_b32_e32 v86, v84
	v_pk_add_f32 v[68:69], v[80:81], v[76:77] neg_lo:[0,1] neg_hi:[0,1]
	v_mov_b32_e32 v85, v71
	v_pk_add_f32 v[76:77], v[86:87], v[68:69]
	s_nop 0
	v_pk_add_f32 v[80:81], v[76:77], v[76:77] op_sel:[0,1] op_sel_hi:[1,0]
	s_nop 0
	v_pk_add_f32 v[70:71], v[70:71], v[80:81] op_sel:[1,0] op_sel_hi:[0,1]
	v_mov_b32_e32 v77, v70
	v_pk_add_f32 v[82:83], v[76:77], v[84:85] neg_lo:[0,1] neg_hi:[0,1]
	v_mov_b32_e32 v69, v80
	v_sub_f32_e32 v71, v76, v82
	v_pk_add_f32 v[68:69], v[68:69], v[82:83] neg_lo:[0,1] neg_hi:[0,1]
	v_sub_f32_e32 v71, v84, v71
	v_add_f32_e32 v68, v68, v71
	v_add_f32_e32 v68, v68, v69
	v_add_f32_e32 v68, v70, v68
	v_cndmask_b32_e32 v68, v114, v68, vcc
	v_cmp_ngt_f32_e32 vcc, -1.0, v64
	s_nop 1
	v_cndmask_b32_e32 v68, v115, v68, vcc
	v_cmp_neq_f32_e32 vcc, -1.0, v64
	s_nop 1
	v_cndmask_b32_e32 v68, v116, v68, vcc
	v_cmp_lt_f32_e64 vcc, |v64|, s61
	s_nop 1
	v_cndmask_b32_e32 v64, v68, v64, vcc

; __device__ __forceinline__ float sigmoidf_(float x) { return 1.f / (1.f + __expf(-x)); }
; __device__ __forceinline__ void phase1(const Params& p, unsigned char* smem) {
;     ...
;           for (int h = 0; h < 8; ++h) {
;             size_t o = (size_t)(bb * 8 + h) * LPAD + pos + 48;
;             if (!isg) BETA[o] = sigmoidf_(v[h]);
;             else { float z = v[h] + p.dt_bias[h]; float sp = z > 20.f ? z : log1pf(__expf(z)); GG[o] = -__expf(p.a_log[h]) * sp; }
.LBB0_192:
	s_or_saveexec_b64 s[40:41], s[40:41]
	v_mov_b64_e32 v[68:69], 0xee1d000
	s_xor_b64 exec, exec, s[40:41]
	s_cbranch_execz .LBB0_196
	v_mov_b32_e32 v64, s81
	s_nop 0
	v_add_f32_e32 v64, v65, v64
	v_cmp_nlt_f32_e32 vcc, s57, v64
	s_and_saveexec_b64 s[42:43], vcc
	s_cbranch_execz .LBB0_195
	v_mul_f32_e32 v64, 0x3fb8aa3b, v64
	v_exp_f32_e32 v79, v64
	s_nop 0
	v_add_f32_e32 v68, 1.0, v79
	v_frexp_mant_f32_e32 v70, v68
	v_cvt_f64_f32_e32 v[64:65], v68
	v_frexp_exp_i32_f64_e32 v64, v[64:65]
	v_cmp_gt_f32_e32 vcc, s58, v70
	v_add_f32_e32 v69, -1.0, v68
	v_sub_f32_e32 v71, v69, v68
	v_subbrev_co_u32_e32 v80, vcc, 0, v64, vcc
	v_sub_u32_e32 v64, 0, v80
	v_sub_f32_e32 v69, v79, v69
	v_add_f32_e32 v71, 1.0, v71
	v_ldexp_f32 v65, v68, v64
	v_add_f32_e32 v69, v69, v71
	v_add_f32_e32 v68, -1.0, v65
	v_add_f32_e32 v70, 1.0, v65
	v_ldexp_f32 v64, v69, v64
	v_add_f32_e32 v69, 1.0, v68
	v_add_f32_e32 v71, -1.0, v70
	v_sub_f32_e32 v69, v65, v69
	v_sub_f32_e32 v65, v65, v71
	v_add_f32_e32 v69, v64, v69
	v_add_f32_e32 v64, v64, v65
	v_add_f32_e32 v81, v70, v64
	v_rcp_f32_e32 v83, v81
	v_sub_f32_e32 v65, v81, v70
	v_sub_f32_e32 v82, v64, v65
	v_add_f32_e32 v65, v68, v69
	v_mul_f32_e32 v85, v65, v83
	v_sub_f32_e32 v64, v65, v68
	v_mul_f32_e32 v68, v81, v85
	v_fma_f32 v70, v85, v81, -v68
	v_fmac_f32_e32 v70, v85, v82
	v_sub_f32_e32 v84, v69, v64
	v_add_f32_e32 v64, v68, v70
	v_sub_f32_e32 v69, v65, v64
	v_pk_add_f32 v[76:77], v[64:65], v[68:69] neg_lo:[0,1] neg_hi:[0,1]
	v_mov_b32_e32 v71, v64
	v_pk_add_f32 v[64:65], v[76:77], v[70:71] neg_lo:[0,1] neg_hi:[0,1]
	v_cmp_neq_f32_e32 vcc, s60, v79
	v_add_f32_e32 v65, v84, v65
	v_add_f32_e32 v64, v64, v65
	v_add_f32_e32 v65, v69, v64
	v_mul_f32_e32 v84, v83, v65
	v_mul_f32_e32 v68, v81, v84
	v_fma_f32 v70, v84, v81, -v68
	v_fmac_f32_e32 v70, v84, v82
	v_sub_f32_e32 v69, v69, v65
	v_add_f32_e32 v81, v64, v69
	v_add_f32_e32 v64, v68, v70
	v_sub_f32_e32 v69, v65, v64
	v_pk_add_f32 v[76:77], v[64:65], v[68:69] neg_lo:[0,1] neg_hi:[0,1]
	v_mov_b32_e32 v71, v64
	v_pk_add_f32 v[64:65], v[76:77], v[70:71] neg_lo:[0,1] neg_hi:[0,1]
	s_nop 0
	v_add_f32_e32 v65, v81, v65
	v_add_f32_e32 v64, v64, v65
	v_add_f32_e32 v65, v85, v84
	v_add_f32_e32 v64, v69, v64
	v_sub_f32_e32 v68, v65, v85
	v_mul_f32_e32 v64, v83, v64
	v_sub_f32_e32 v68, v84, v68
	v_add_f32_e32 v68, v68, v64
	v_add_f32_e32 v70, v65, v68
	v_mul_f32_e32 v71, v70, v70
	v_fmamk_f32 v64, v71, 0x3e9b6dac, v110
	v_fmaak_f32 v99, v71, v64, 0x3f2aaada
	v_cvt_f32_i32_e32 v64, v80
	v_sub_f32_e32 v65, v70, v65
	v_sub_f32_e32 v65, v68, v65
	v_ldexp_f32 v76, v65, 1
	v_mul_f32_e32 v65, v70, v71
	v_ldexp_f32 v69, v70, 1
	v_pk_mul_f32 v[70:71], v[64:65], v[98:99]
	s_nop 0
	v_fma_f32 v68, v64, s59, -v70
	v_fmac_f32_e32 v68, 0xb102e308, v64
	v_pk_add_f32 v[64:65], v[70:71], v[68:69]
	s_nop 0
	v_sub_f32_e32 v69, v65, v69
	v_sub_f32_e32 v69, v71, v69
	v_add_f32_e32 v77, v76, v69
	v_mov_b32_e32 v76, v70
	v_pk_add_f32 v[70:71], v[64:65], v[70:71] neg_lo:[0,1] neg_hi:[0,1]
	v_pk_add_f32 v[80:81], v[64:65], v[76:77]
	v_mov_b32_e32 v69, v64
	v_mov_b32_e32 v71, v81
	v_pk_add_f32 v[82:83], v[68:69], v[70:71] neg_lo:[0,1] neg_hi:[0,1]
	v_pk_add_f32 v[68:69], v[68:69], v[70:71]
	v_mov_b32_e32 v76, v77
	v_pk_add_f32 v[70:71], v[68:69], v[64:65] op_sel:[1,0] op_sel_hi:[0,1] neg_lo:[0,1] neg_hi:[0,1]
	v_pk_add_f32 v[84:85], v[80:81], v[70:71] op_sel_hi:[1,0] neg_lo:[0,1] neg_hi:[0,1]
	v_mov_b32_e32 v80, v81
	v_mov_b32_e32 v81, v69
	v_pk_mov_b32 v[70:71], v[64:65], v[70:71] op_sel:[1,0]
	v_mov_b32_e32 v77, v64
	v_pk_add_f32 v[70:71], v[80:81], v[70:71] neg_lo:[0,1] neg_hi:[0,1]
	v_mov_b32_e32 v84, v82
	v_pk_add_f32 v[64:65], v[76:77], v[70:71] neg_lo:[0,1] neg_hi:[0,1]
	v_mov_b32_e32 v83, v69
	v_pk_add_f32 v[70:71], v[84:85], v[64:65]
	s_nop 0
	v_pk_add_f32 v[76:77], v[70:71], v[70:71] op_sel:[0,1] op_sel_hi:[1,0]
	s_nop 0
	v_pk_add_f32 v[68:69], v[68:69], v[76:77] op_sel:[1,0] op_sel_hi:[0,1]
	v_mov_b32_e32 v71, v68
	v_pk_add_f32 v[80:81], v[70:71], v[82:83] neg_lo:[0,1] neg_hi:[0,1]
	v_mov_b32_e32 v65, v76
	v_sub_f32_e32 v69, v70, v80
	v_pk_add_f32 v[64:65], v[64:65], v[80:81] neg_lo:[0,1] neg_hi:[0,1]
	v_sub_f32_e32 v69, v82, v69
	v_add_f32_e32 v64, v64, v69
	v_add_f32_e32 v64, v64, v65
	v_add_f32_e32 v64, v68, v64
	v_cndmask_b32_e32 v64, v114, v64, vcc
	v_cmp_ngt_f32_e32 vcc, -1.0, v79
	s_nop 1
	v_cndmask_b32_e32 v64, v115, v64, vcc
	v_cmp_neq_f32_e32 vcc, -1.0, v79
	s_nop 1
	v_cndmask_b32_e32 v64, v116, v64, vcc
	v_cmp_lt_f32_e64 vcc, |v79|, s61
	s_nop 1
	v_cndmask_b32_e32 v64, v64, v79, vcc

; __device__ __forceinline__ float sigmoidf_(float x) { return 1.f / (1.f + __expf(-x)); }
; __device__ __forceinline__ void phase1(const Params& p, unsigned char* smem) {
;     ...
;           for (int h = 0; h < 8; ++h) {
;             size_t o = (size_t)(bb * 8 + h) * LPAD + pos + 48;
;             if (!isg) BETA[o] = sigmoidf_(v[h]);
;             else { float z = v[h] + p.dt_bias[h]; float sp = z > 20.f ? z : log1pf(__expf(z)); GG[o] = -__expf(p.a_log[h]) * sp; }
.LBB0_198:
	s_or_saveexec_b64 s[40:41], s[40:41]
	v_mov_b64_e32 v[64:65], 0xee1d000
	s_xor_b64 exec, exec, s[40:41]
	s_cbranch_execz .LBB0_202
	v_mov_b32_e32 v64, s82
	s_nop 0
	v_add_f32_e32 v64, v66, v64
	v_cmp_nlt_f32_e32 vcc, s57, v64
	s_and_saveexec_b64 s[42:43], vcc
	s_cbranch_execz .LBB0_201
	v_mul_f32_e32 v64, 0x3fb8aa3b, v64
	v_exp_f32_e32 v66, v64
	s_nop 0
	v_add_f32_e32 v68, 1.0, v66
	v_frexp_mant_f32_e32 v70, v68
	v_cvt_f64_f32_e32 v[64:65], v68
	v_frexp_exp_i32_f64_e32 v64, v[64:65]
	v_cmp_gt_f32_e32 vcc, s58, v70
	v_add_f32_e32 v69, -1.0, v68
	v_sub_f32_e32 v71, v69, v68
	v_subbrev_co_u32_e32 v79, vcc, 0, v64, vcc
	v_sub_u32_e32 v64, 0, v79
	v_sub_f32_e32 v69, v66, v69
	v_add_f32_e32 v71, 1.0, v71
	v_ldexp_f32 v65, v68, v64
	v_add_f32_e32 v69, v69, v71
	v_add_f32_e32 v68, -1.0, v65
	v_add_f32_e32 v70, 1.0, v65
	v_ldexp_f32 v64, v69, v64
	v_add_f32_e32 v69, 1.0, v68
	v_add_f32_e32 v71, -1.0, v70
	v_sub_f32_e32 v69, v65, v69
	v_sub_f32_e32 v65, v65, v71
	v_add_f32_e32 v69, v64, v69
	v_add_f32_e32 v64, v64, v65
	v_add_f32_e32 v80, v70, v64
	v_rcp_f32_e32 v82, v80
	v_sub_f32_e32 v65, v80, v70
	v_sub_f32_e32 v81, v64, v65
	v_add_f32_e32 v65, v68, v69
	v_mul_f32_e32 v84, v65, v82
	v_sub_f32_e32 v64, v65, v68
	v_mul_f32_e32 v68, v80, v84
	v_fma_f32 v70, v84, v80, -v68
	v_fmac_f32_e32 v70, v84, v81
	v_sub_f32_e32 v83, v69, v64
	v_add_f32_e32 v64, v68, v70
	v_sub_f32_e32 v69, v65, v64
	v_pk_add_f32 v[76:77], v[64:65], v[68:69] neg_lo:[0,1] neg_hi:[0,1]
	v_mov_b32_e32 v71, v64
	v_pk_add_f32 v[64:65], v[76:77], v[70:71] neg_lo:[0,1] neg_hi:[0,1]
	v_cmp_neq_f32_e32 vcc, s60, v66
	v_add_f32_e32 v65, v83, v65
	v_add_f32_e32 v64, v64, v65
	v_add_f32_e32 v65, v69, v64
	v_mul_f32_e32 v83, v82, v65
	v_mul_f32_e32 v68, v80, v83
	v_fma_f32 v70, v83, v80, -v68
	v_fmac_f32_e32 v70, v83, v81
	v_sub_f32_e32 v69, v69, v65
	v_add_f32_e32 v80, v64, v69
	v_add_f32_e32 v64, v68, v70
	v_sub_f32_e32 v69, v65, v64
	v_pk_add_f32 v[76:77], v[64:65], v[68:69] neg_lo:[0,1] neg_hi:[0,1]
	v_mov_b32_e32 v71, v64
	v_pk_add_f32 v[64:65], v[76:77], v[70:71] neg_lo:[0,1] neg_hi:[0,1]
	s_nop 0
	v_add_f32_e32 v65, v80, v65
	v_add_f32_e32 v64, v64, v65
	v_add_f32_e32 v65, v84, v83
	v_add_f32_e32 v64, v69, v64
	v_sub_f32_e32 v68, v65, v84
	v_mul_f32_e32 v64, v82, v64
	v_sub_f32_e32 v68, v83, v68
	v_add_f32_e32 v68, v68, v64
	v_add_f32_e32 v70, v65, v68
	v_mul_f32_e32 v71, v70, v70
	v_fmamk_f32 v64, v71, 0x3e9b6dac, v110
	v_fmaak_f32 v99, v71, v64, 0x3f2aaada
	v_cvt_f32_i32_e32 v64, v79
	v_sub_f32_e32 v65, v70, v65
	v_sub_f32_e32 v65, v68, v65
	v_ldexp_f32 v76, v65, 1
	v_mul_f32_e32 v65, v70, v71
	v_ldexp_f32 v69, v70, 1
	v_pk_mul_f32 v[70:71], v[64:65], v[98:99]
	s_nop 0
	v_fma_f32 v68, v64, s59, -v70
	v_fmac_f32_e32 v68, 0xb102e308, v64
	v_pk_add_f32 v[64:65], v[70:71], v[68:69]
	s_nop 0
	v_sub_f32_e32 v69, v65, v69
	v_sub_f32_e32 v69, v71, v69
	v_add_f32_e32 v77, v76, v69
	v_mov_b32_e32 v76, v70
	v_pk_add_f32 v[70:71], v[64:65], v[70:71] neg_lo:[0,1] neg_hi:[0,1]
	v_pk_add_f32 v[80:81], v[64:65], v[76:77]
	v_mov_b32_e32 v69, v64
	v_mov_b32_e32 v71, v81
	v_pk_add_f32 v[82:83], v[68:69], v[70:71] neg_lo:[0,1] neg_hi:[0,1]
	v_pk_add_f32 v[68:69], v[68:69], v[70:71]
	v_mov_b32_e32 v76, v77
	v_pk_add_f32 v[70:71], v[68:69], v[64:65] op_sel:[1,0] op_sel_hi:[0,1] neg_lo:[0,1] neg_hi:[0,1]
	v_pk_add_f32 v[84:85], v[80:81], v[70:71] op_sel_hi:[1,0] neg_lo:[0,1] neg_hi:[0,1]
	v_mov_b32_e32 v80, v81
	v_mov_b32_e32 v81, v69
	v_pk_mov_b32 v[70:71], v[64:65], v[70:71] op_sel:[1,0]
	v_mov_b32_e32 v77, v64
	v_pk_add_f32 v[70:71], v[80:81], v[70:71] neg_lo:[0,1] neg_hi:[0,1]
	v_mov_b32_e32 v84, v82
	v_pk_add_f32 v[64:65], v[76:77], v[70:71] neg_lo:[0,1] neg_hi:[0,1]
	v_mov_b32_e32 v83, v69
	v_pk_add_f32 v[70:71], v[84:85], v[64:65]
	s_nop 0
	v_pk_add_f32 v[76:77], v[70:71], v[70:71] op_sel:[0,1] op_sel_hi:[1,0]
	s_nop 0
	v_pk_add_f32 v[68:69], v[68:69], v[76:77] op_sel:[1,0] op_sel_hi:[0,1]
	v_mov_b32_e32 v71, v68
	v_pk_add_f32 v[80:81], v[70:71], v[82:83] neg_lo:[0,1] neg_hi:[0,1]
	v_mov_b32_e32 v65, v76
	v_sub_f32_e32 v69, v70, v80
	v_pk_add_f32 v[64:65], v[64:65], v[80:81] neg_lo:[0,1] neg_hi:[0,1]
	v_sub_f32_e32 v69, v82, v69
	v_add_f32_e32 v64, v64, v69
	v_add_f32_e32 v64, v64, v65
	v_add_f32_e32 v64, v68, v64
	v_cndmask_b32_e32 v64, v114, v64, vcc
	v_cmp_ngt_f32_e32 vcc, -1.0, v66
	s_nop 1
	v_cndmask_b32_e32 v64, v115, v64, vcc
	v_cmp_neq_f32_e32 vcc, -1.0, v66
	s_nop 1
	v_cndmask_b32_e32 v64, v116, v64, vcc
	v_cmp_lt_f32_e64 vcc, |v66|, s61
	s_nop 1
	v_cndmask_b32_e32 v64, v64, v66, vcc

; __device__ __forceinline__ float sigmoidf_(float x) { return 1.f / (1.f + __expf(-x)); }
; __device__ __forceinline__ void phase1(const Params& p, unsigned char* smem) {
;     ...
;           for (int h = 0; h < 8; ++h) {
;             size_t o = (size_t)(bb * 8 + h) * LPAD + pos + 48;
;             if (!isg) BETA[o] = sigmoidf_(v[h]);
;             else { float z = v[h] + p.dt_bias[h]; float sp = z > 20.f ? z : log1pf(__expf(z)); GG[o] = -__expf(p.a_log[h]) * sp; }
.LBB0_204:
	s_or_saveexec_b64 s[40:41], s[40:41]
	v_mov_b64_e32 v[64:65], 0xee1d000
	s_xor_b64 exec, exec, s[40:41]
	s_cbranch_execz .LBB0_107
	v_mov_b32_e32 v64, s83
	s_nop 0
	v_add_f32_e32 v64, v67, v64
	v_cmp_nlt_f32_e32 vcc, s57, v64
	s_and_saveexec_b64 s[42:43], vcc
	s_cbranch_execz .LBB0_106
	v_mul_f32_e32 v64, 0x3fb8aa3b, v64
	v_exp_f32_e32 v79, v64
	s_nop 0
	v_add_f32_e32 v66, 1.0, v79
	v_frexp_mant_f32_e32 v68, v66
	v_cvt_f64_f32_e32 v[64:65], v66
	v_frexp_exp_i32_f64_e32 v64, v[64:65]
	v_cmp_gt_f32_e32 vcc, s58, v68
	v_add_f32_e32 v67, -1.0, v66
	v_sub_f32_e32 v69, v67, v66
	v_subbrev_co_u32_e32 v76, vcc, 0, v64, vcc
	v_sub_u32_e32 v64, 0, v76
	v_sub_f32_e32 v67, v79, v67
	v_add_f32_e32 v69, 1.0, v69
	v_ldexp_f32 v65, v66, v64
	v_add_f32_e32 v67, v67, v69
	v_add_f32_e32 v66, -1.0, v65
	v_add_f32_e32 v68, 1.0, v65
	v_ldexp_f32 v64, v67, v64
	v_add_f32_e32 v67, 1.0, v66
	v_add_f32_e32 v69, -1.0, v68
	v_sub_f32_e32 v67, v65, v67
	v_sub_f32_e32 v65, v65, v69
	v_add_f32_e32 v67, v64, v67
	v_add_f32_e32 v64, v64, v65
	v_add_f32_e32 v77, v68, v64
	v_rcp_f32_e32 v81, v77
	v_sub_f32_e32 v65, v77, v68
	v_sub_f32_e32 v80, v64, v65
	v_add_f32_e32 v65, v66, v67
	v_mul_f32_e32 v83, v65, v81
	v_sub_f32_e32 v64, v65, v66
	v_mul_f32_e32 v66, v77, v83
	v_fma_f32 v68, v83, v77, -v66
	v_fmac_f32_e32 v68, v83, v80
	v_sub_f32_e32 v82, v67, v64
	v_add_f32_e32 v64, v66, v68
	v_sub_f32_e32 v67, v65, v64
	v_pk_add_f32 v[70:71], v[64:65], v[66:67] neg_lo:[0,1] neg_hi:[0,1]
	v_mov_b32_e32 v69, v64
	v_pk_add_f32 v[64:65], v[70:71], v[68:69] neg_lo:[0,1] neg_hi:[0,1]
	v_cmp_neq_f32_e32 vcc, s60, v79
	v_add_f32_e32 v65, v82, v65
	v_add_f32_e32 v64, v64, v65
	v_add_f32_e32 v65, v67, v64
	v_mul_f32_e32 v82, v81, v65
	v_mul_f32_e32 v66, v77, v82
	v_fma_f32 v68, v82, v77, -v66
	v_fmac_f32_e32 v68, v82, v80
	v_sub_f32_e32 v67, v67, v65
	v_add_f32_e32 v77, v64, v67
	v_add_f32_e32 v64, v66, v68
	v_sub_f32_e32 v67, v65, v64
	v_pk_add_f32 v[70:71], v[64:65], v[66:67] neg_lo:[0,1] neg_hi:[0,1]
	v_mov_b32_e32 v69, v64
	v_pk_add_f32 v[64:65], v[70:71], v[68:69] neg_lo:[0,1] neg_hi:[0,1]
	s_nop 0
	v_add_f32_e32 v65, v77, v65
	v_add_f32_e32 v64, v64, v65
	v_add_f32_e32 v65, v83, v82
	v_add_f32_e32 v64, v67, v64
	v_sub_f32_e32 v66, v65, v83
	v_mul_f32_e32 v64, v81, v64
	v_sub_f32_e32 v66, v82, v66
	v_add_f32_e32 v66, v66, v64
	v_add_f32_e32 v68, v65, v66
	v_mul_f32_e32 v69, v68, v68
	v_fmamk_f32 v64, v69, 0x3e9b6dac, v110
	v_fmaak_f32 v99, v69, v64, 0x3f2aaada
	v_cvt_f32_i32_e32 v64, v76
	v_sub_f32_e32 v65, v68, v65
	v_sub_f32_e32 v65, v66, v65
	v_ldexp_f32 v70, v65, 1
	v_mul_f32_e32 v65, v68, v69
	v_ldexp_f32 v67, v68, 1
	v_pk_mul_f32 v[68:69], v[64:65], v[98:99]
	s_nop 0
	v_fma_f32 v66, v64, s59, -v68
	v_fmac_f32_e32 v66, 0xb102e308, v64
	v_pk_add_f32 v[64:65], v[68:69], v[66:67]
	s_nop 0
	v_sub_f32_e32 v67, v65, v67
	v_sub_f32_e32 v67, v69, v67
	v_add_f32_e32 v71, v70, v67
	v_mov_b32_e32 v70, v68
	v_pk_add_f32 v[68:69], v[64:65], v[68:69] neg_lo:[0,1] neg_hi:[0,1]
	v_pk_add_f32 v[76:77], v[64:65], v[70:71]
	v_mov_b32_e32 v67, v64
	v_mov_b32_e32 v69, v77
	v_pk_add_f32 v[80:81], v[66:67], v[68:69] neg_lo:[0,1] neg_hi:[0,1]
	v_pk_add_f32 v[66:67], v[66:67], v[68:69]
	v_mov_b32_e32 v70, v71
	v_pk_add_f32 v[68:69], v[66:67], v[64:65] op_sel:[1,0] op_sel_hi:[0,1] neg_lo:[0,1] neg_hi:[0,1]
	v_pk_add_f32 v[82:83], v[76:77], v[68:69] op_sel_hi:[1,0] neg_lo:[0,1] neg_hi:[0,1]
	v_mov_b32_e32 v76, v77
	v_mov_b32_e32 v77, v67
	v_pk_mov_b32 v[68:69], v[64:65], v[68:69] op_sel:[1,0]
	v_mov_b32_e32 v71, v64
	v_pk_add_f32 v[68:69], v[76:77], v[68:69] neg_lo:[0,1] neg_hi:[0,1]
	v_mov_b32_e32 v82, v80
	v_pk_add_f32 v[64:65], v[70:71], v[68:69] neg_lo:[0,1] neg_hi:[0,1]
	v_mov_b32_e32 v81, v67
	v_pk_add_f32 v[68:69], v[82:83], v[64:65]
	s_nop 0
	v_pk_add_f32 v[70:71], v[68:69], v[68:69] op_sel:[0,1] op_sel_hi:[1,0]
	s_nop 0
	v_pk_add_f32 v[66:67], v[66:67], v[70:71] op_sel:[1,0] op_sel_hi:[0,1]
	v_mov_b32_e32 v69, v66
	v_pk_add_f32 v[76:77], v[68:69], v[80:81] neg_lo:[0,1] neg_hi:[0,1]
	v_mov_b32_e32 v65, v70
	v_sub_f32_e32 v67, v68, v76
	v_pk_add_f32 v[64:65], v[64:65], v[76:77] neg_lo:[0,1] neg_hi:[0,1]
	v_sub_f32_e32 v67, v80, v67
	v_add_f32_e32 v64, v64, v67
	v_add_f32_e32 v64, v64, v65
	v_add_f32_e32 v64, v66, v64
	v_cndmask_b32_e32 v64, v114, v64, vcc
	v_cmp_ngt_f32_e32 vcc, -1.0, v79
	s_nop 1
	v_cndmask_b32_e32 v64, v115, v64, vcc
	v_cmp_neq_f32_e32 vcc, -1.0, v79
	s_nop 1
	v_cndmask_b32_e32 v64, v116, v64, vcc
	v_cmp_lt_f32_e64 vcc, |v79|, s61
	s_nop 1
	v_cndmask_b32_e32 v64, v64, v79, vcc
	s_branch .LBB0_106

; __device__ __forceinline__ float bflo(unsigned v) { return __uint_as_float(v << 16); }
; __device__ __forceinline__ float bfhi(unsigned v) { return __uint_as_float(v & 0xffff0000u); }
; __device__ __forceinline__ void grid_barrier(unsigned* ctr, const unsigned k) {
;   __syncthreads();
;   if (threadIdx.x == 0) {
;     __hip_atomic_fetch_add(ctr, 1u, __ATOMIC_RELEASE, __HIP_MEMORY_SCOPE_AGENT);
;     const unsigned target = k * gridDim.x;
;     while (__hip_atomic_load(ctr, __ATOMIC_RELAXED, __HIP_MEMORY_SCOPE_AGENT) < target) __builtin_amdgcn_s_sleep(1);
;     __builtin_amdgcn_fence(__ATOMIC_ACQUIRE, "agent");
;   }
;   __syncthreads();
; }
; template <bool SIGNAL>
; __device__ __forceinline__ void phase2(const Params& p, unsigned char* smem, const int lo, const int hi, const int worker, const int nworkers) {
;     ...
;       {
;         u32x4 ld[5];
; #pragma unroll
;         for (int i = 0; i < 5; ++i) {
;           const int idx = tid + 256 * i; const int rr = idx >> 4, c8 = (idx & 15) * 8; const int r = rr - 3;
;           const bool zero = (idx >= 67 * 16) || (c == 0 && r < 48);
;           const u16* srcp = (r < 0) ? (H + rr * 128 + c8) : (X + r * 128 + c8);
;           u32x4 z = {0u, 0u, 0u, 0u};
;           ld[i] = zero ? z : *(const u32x4*)srcp;
;         }
; #pragma unroll
;         for (int i = 0; i < 5; ++i) {
;           const int idx = tid + 256 * i; const int rr = idx >> 4, c8 = (idx & 15) * 8;
;           if (idx < 67 * 16) {
;             float4 a = make_float4(bflo(ld[i].x), bfhi(ld[i].x), bflo(ld[i].y), bfhi(ld[i].y));
;             float4 b = make_float4(bflo(ld[i].z), bfhi(ld[i].z), bflo(ld[i].w), bfhi(ld[i].w));
;             *(float4*)(sin + rr * 128 + c8) = a; *(float4*)(sin + rr * 128 + c8 + 4) = b;
;           }
;         }
.LBB0_244:
	s_add_u32 s44, s50, 0xf223800
	s_addc_u32 s45, s51, 0
	v_cmp_eq_u32_e64 s[12:13], 0, v218
	s_barrier
	s_and_saveexec_b64 s[4:5], s[12:13]
	s_cbranch_execz .LBB0_250
	buffer_wbl2 sc1
	s_waitcnt vmcnt(0)
	v_mov_b32_e32 v0, 0
	v_mov_b32_e32 v1, 1
	global_atomic_add v1, v0, v1, s[44:45] sc0
	s_waitcnt vmcnt(0)
	v_readfirstlane_b32 s6, v1
	s_nop 3
	s_add_i32 s6, s6, 1
	s_cmp_eq_u32 s6, s3
	s_cbranch_scc0 .Lgbar2_poll
	v_mov_b32_e32 v1, 1
	global_atomic_add v0, v1, s[44:45] offset:1280
	global_atomic_add v0, v1, s[44:45] offset:1344
	global_atomic_add v0, v1, s[44:45] offset:1408
	global_atomic_add v0, v1, s[44:45] offset:1472
	global_atomic_add v0, v1, s[44:45] offset:1536
	global_atomic_add v0, v1, s[44:45] offset:1600
	global_atomic_add v0, v1, s[44:45] offset:1664
	global_atomic_add v0, v1, s[44:45] offset:1728
	s_branch .Lgbar2_done
.Lgbar2_poll:
	s_and_b32 s6, s89, 7
	s_lshl_b32 s6, s6, 6
	v_mov_b32_e32 v0, s6
.Lgbar2_loop:
	global_load_dword v1, v0, s[44:45] offset:1280 sc1
	s_waitcnt vmcnt(0)
	v_cmp_le_u32_e32 vcc, 2, v1
	s_cbranch_vccnz .Lgbar2_done
	s_sleep 2
	s_branch .Lgbar2_loop
.Lgbar2_done:
	buffer_inv sc1
	s_waitcnt vmcnt(0)
.LBB0_250:
	s_or_b64 exec, exec, s[4:5]
	v_mov_b32_e32 v220, v218
	v_writelane_b32 v247, s12, 0
	s_cmp_gt_u32 s89, 15
	s_mov_b64 s[4:5], -1
	v_writelane_b32 v247, s13, 1
	s_barrier
	s_cbranch_scc0 .LBB0_311
	s_add_i32 s84, s89, -16
	v_mov_b32_e32 v32, v218
	s_cmpk_gt_i32 s84, 0xf7
	v_writelane_b32 v247, s73, 2
	s_cbranch_scc1 .LBB0_310
	s_load_dwordx2 s[6:7], s[0:1], 0x90
	v_lshlrev_b32_e32 v7, 3, v32
	v_and_b32_e32 v0, 0x78, v7
	v_mov_b32_e32 v35, 0
	v_lshlrev_b32_e32 v34, 1, v0
	s_waitcnt lgkmcnt(0)
	s_add_u32 s85, s6, 0x6090000
	s_addc_u32 s86, s7, 0
	s_add_u32 s2, s6, 0xee1d000
	v_writelane_b32 v247, s2, 3
	s_addc_u32 s2, s7, 0
	v_writelane_b32 v247, s2, 4
	s_add_u32 s2, s6, 0xee9e000
	v_writelane_b32 v247, s2, 5
	s_addc_u32 s2, s7, 0
	v_writelane_b32 v247, s2, 6
	s_add_u32 s2, s6, 0xc5d9000
	v_writelane_b32 v247, s2, 7
	s_addc_u32 s2, s7, 0
	v_lshl_add_u64 v[4:5], s[6:7], 0, v[34:35]
	s_mov_b64 s[12:13], 0xc150000
	v_writelane_b32 v247, s2, 8
	v_lshl_add_u64 v[36:37], v[4:5], 0, s[12:13]
	v_cmp_gt_i32_e64 s[12:13], 64, v32
	v_and_b32_e32 v39, 63, v32
	v_ashrrev_i32_e32 v2, 6, v32
	v_writelane_b32 v247, s12, 9
	v_and_b32_e32 v1, 31, v32
	v_and_b32_e32 v38, 56, v7
	v_writelane_b32 v247, s13, 10
	v_cmp_eq_u32_e64 s[12:13], 0, v32
	v_lshlrev_b32_e32 v7, 5, v2
	v_and_or_b32 v1, v7, 32, v1
	v_writelane_b32 v247, s12, 11
	s_movk_i32 s11, 0x110
	v_ashrrev_i32_e32 v13, 2, v32
	v_writelane_b32 v247, s13, 12
	v_cmp_eq_u32_e64 s[12:13], 0, v39
	s_movk_i32 s8, 0xffe0
	v_bfe_u32 v6, v32, 5, 1
	v_writelane_b32 v247, s12, 13
	v_mad_u32_u24 v11, v1, s11, 16
	v_and_b32_e32 v14, 0xffffffe0, v13
	v_writelane_b32 v247, s13, 14
	v_cmp_gt_u32_e64 s[12:13], 2, v39
	v_bfi_b32 v13, s8, v13, v32
	s_movk_i32 s8, 0xfef4
	v_writelane_b32 v247, s12, 15
	v_mul_u32_u24_e32 v4, 0x118, v39
	v_lshlrev_b32_e32 v5, 3, v39
	v_writelane_b32 v247, s13, 16
	v_cmp_gt_u32_e64 s[12:13], 4, v39
	v_lshl_add_u32 v10, v38, 1, 16
	v_lshlrev_b32_e32 v12, 4, v6
	v_writelane_b32 v247, s12, 17
	v_lshl_or_b32 v20, v6, 2, v14
	v_mad_i32_i24 v6, v1, s8, v11
	v_writelane_b32 v247, s13, 18
	v_cmp_gt_u32_e64 s[12:13], 8, v39
	s_movk_i32 s8, 0x10e
	v_add3_u32 v9, 16, v5, v4
	v_writelane_b32 v247, s12, 19
	v_add_u32_e32 v108, v11, v12
	v_lshlrev_b32_e32 v11, 4, v39
	v_writelane_b32 v247, s13, 20
	v_cmp_gt_u32_e64 s[12:13], 16, v39
	v_mad_u32_u24 v21, v38, s8, v10
	s_movk_i32 s8, 0x42f
	v_writelane_b32 v247, s12, 21
	s_add_i32 s9, 16, 0x10e00
	s_add_i32 s10, 16, 0x10f00
	v_writelane_b32 v247, s13, 22
	v_cmp_gt_u32_e64 s[12:13], 32, v39
	v_sub_u32_e32 v111, v9, v11
	v_lshlrev_b32_e32 v9, 2, v32
	v_writelane_b32 v247, s12, 23
	v_add_u32_e32 v112, s9, v9
	v_add_u32_e32 v113, s10, v9
	v_writelane_b32 v247, s13, 24
	v_cmp_lt_i32_e64 s[12:13], s8, v32
	v_ashrrev_i32_e32 v9, 4, v32
	s_movk_i32 s8, 0x32f
	v_writelane_b32 v247, s12, 25
	v_cmp_gt_i32_e64 s[26:27], 3, v9
	v_lshlrev_b32_e32 v42, 7, v9
	v_writelane_b32 v247, s13, 26
	v_cmp_gt_i32_e64 s[12:13], 51, v9
	v_add_u32_e32 v9, 0x100, v32
	v_ashrrev_i32_e32 v11, 4, v9
	v_writelane_b32 v247, s12, 27
	v_mul_lo_u32 v13, v13, s11
	v_cmp_gt_i32_e64 s[34:35], 3, v11
	v_writelane_b32 v247, s13, 28
	v_cmp_lt_i32_e64 s[12:13], s8, v32
	s_movk_i32 s8, 0x22f
	v_lshlrev_b32_e32 v46, 7, v11
	v_writelane_b32 v247, s12, 29
	v_add3_u32 v109, 16, v13, v12
	v_lshl_add_u32 v8, v0, 2, 16
	v_writelane_b32 v247, s13, 30
	v_cmp_gt_i32_e64 s[12:13], 51, v11
	v_add_u32_e32 v11, 0x200, v32
	v_ashrrev_i32_e32 v12, 4, v11
	v_writelane_b32 v247, s12, 31
	v_cmp_gt_i32_e64 s[40:41], 3, v12
	v_lshlrev_b32_e32 v50, 7, v12
	v_writelane_b32 v247, s13, 32
	v_cmp_lt_i32_e64 s[12:13], s8, v32
	s_movk_i32 s8, 0x12f
	v_ashrrev_i32_e32 v22, 3, v32
	v_writelane_b32 v247, s12, 33
	v_ashrrev_i32_e32 v23, 3, v9
	v_lshlrev_b32_e32 v62, 6, v22
	v_writelane_b32 v247, s13, 34
	v_cmp_gt_i32_e64 s[12:13], 51, v12
	v_add_u32_e32 v12, 0x300, v32
	v_ashrrev_i32_e32 v13, 4, v12
	v_writelane_b32 v247, s12, 35
	v_cmp_gt_i32_e64 s[46:47], 3, v13
	v_lshlrev_b32_e32 v54, 7, v13
	v_writelane_b32 v247, s13, 36
	v_cmp_lt_i32_e64 s[12:13], s8, v32
	s_movk_i32 s8, 0x430
	v_cmp_gt_i32_e64 s[54:55], s8, v32
	v_writelane_b32 v247, s12, 37
	s_movk_i32 s8, 0x330
	v_cmp_gt_i32_e64 s[56:57], s8, v32
	v_writelane_b32 v247, s13, 38
	v_cmp_gt_i32_e64 s[12:13], 51, v13
	v_add_u32_e32 v13, 0x400, v32
	v_ashrrev_i32_e32 v14, 4, v13
	v_writelane_b32 v247, s12, 39
	v_cmp_gt_i32_e64 s[52:53], 3, v14
	v_lshlrev_b32_e32 v58, 7, v14
	v_writelane_b32 v247, s13, 40
	v_cmp_lt_i32_e64 s[12:13], 47, v32
	s_movk_i32 s8, 0x230
	v_lshlrev_b32_e32 v13, 5, v13
	v_writelane_b32 v247, s12, 41
	v_cmp_gt_i32_e64 s[58:59], s8, v32
	s_movk_i32 s8, 0x130
	v_writelane_b32 v247, s13, 42
	v_cmp_gt_i32_e64 s[12:13], 51, v14
	v_lshlrev_b32_e32 v14, 5, v32
	v_and_b32_e32 v14, 0xfffffe00, v14
	v_add_u32_e32 v114, v8, v14
	v_lshlrev_b32_e32 v14, 5, v9
	v_and_b32_e32 v14, 0xfffffe00, v14
	v_add_u32_e32 v115, v8, v14
	v_lshlrev_b32_e32 v14, 5, v11
	v_and_b32_e32 v14, 0xfffffe00, v14
	v_writelane_b32 v247, s12, 43
	v_add_u32_e32 v116, v8, v14
	v_lshlrev_b32_e32 v14, 5, v12
	v_writelane_b32 v247, s13, 44
	v_and_b32_e32 v14, 0xfffffe00, v14
	v_and_b32_e32 v13, 0xfffffe00, v13
	s_movk_i32 s12, 0x90
	v_cmp_gt_i32_e64 s[60:61], s8, v32
	v_add_u32_e32 v117, v8, v14
	v_add_u32_e32 v118, v8, v13
	v_mul_lo_u32 v8, v22, s12
	s_mov_b32 s8, 0x8600
	v_add3_u32 v119, v10, v8, s8
	v_mul_lo_u32 v8, v23, s12
	v_add3_u32 v120, v10, v8, s8
	v_ashrrev_i32_e32 v8, 3, v11
	v_mul_lo_u32 v9, v8, s12
	s_waitcnt vmcnt(6)
; __device__ __forceinline__ u16 f2bf(float f) { return (u16)(cvtpk(f, 0.f) & 0xffffu); }
; template <bool SIGNAL>
; __device__ __forceinline__ void phase2(const Params& p, unsigned char* smem, const int lo, const int hi, const int worker, const int nworkers) {
;     ...
;     u16* Tg = TA + (size_t)it * 8704; u16* Ag = Tg + 4096; float* SCg = (float*)(Tg + 8192);
;     {
;       const int j = 32 * tj + l31; const float gcj = sgc[j];
; #pragma unroll
;       for (int r = 0; r < 16; ++r) {
;         const int i = 32 * ti + 8 * (r >> 2) + 4 * hf + (r & 3);
;         const float gci = sgc[i]; const float bi = sbeta[i];
;         const float dec = __expf(gci - gcj);
;         sM[i * 68 + j] = (j < i) ? bi * kk[r] * dec : 0.f;
;         Ag[i * 64 + j] = f2bf((j <= i) ? qk[r] * dec : 0.f);
;       }
;     }
	v_lshlrev_b32_e32 v66, 6, v8
	v_ashrrev_i32_e32 v8, 3, v12
	v_add3_u32 v121, v10, v9, s8
	v_mul_lo_u32 v9, v8, s12
	v_cmp_lt_i32_e64 s[12:13], v1, v20
	v_add3_u32 v122, v10, v9, s8
	v_or_b32_e32 v9, 1, v20
	v_writelane_b32 v247, s12, 45
	v_lshlrev_b32_e32 v10, 2, v9
	s_waitcnt vmcnt(5)
	v_lshl_or_b32 v72, v9, 6, v1
	v_writelane_b32 v247, s13, 46
	v_cmp_gt_i32_e64 s[12:13], v1, v9
	v_or_b32_e32 v9, 2, v20
	v_add_u32_e32 v125, s9, v10
	v_writelane_b32 v247, s12, 47
	v_add_u32_e32 v126, s10, v10
	v_lshlrev_b32_e32 v10, 2, v9
	v_writelane_b32 v247, s13, 48
	v_cmp_lt_i32_e64 s[12:13], v1, v9
	v_lshl_or_b32 v74, v9, 6, v1
	v_add_u32_e32 v127, s9, v10
	v_writelane_b32 v247, s12, 49
	v_add_u32_e32 v128, s10, v10
	v_lshlrev_b32_e32 v68, 6, v8
	v_writelane_b32 v247, s13, 50
	v_cmp_gt_i32_e64 s[12:13], v1, v9
	v_or_b32_e32 v9, 3, v20
	v_lshlrev_b32_e32 v10, 2, v9
	v_writelane_b32 v247, s12, 51
	s_waitcnt vmcnt(3)
	v_lshl_or_b32 v76, v9, 6, v1
	v_add_u32_e32 v129, s9, v10
	v_writelane_b32 v247, s13, 52
	v_cmp_lt_i32_e64 s[12:13], v1, v9
	v_add_u32_e32 v130, s10, v10
	v_lshlrev_b32_e32 v8, 2, v20
	v_writelane_b32 v247, s12, 53
	v_add_u32_e32 v123, s9, v8
	v_add_u32_e32 v124, s10, v8
	v_writelane_b32 v247, s13, 54
	v_cmp_gt_i32_e64 s[12:13], v1, v9
	v_or_b32_e32 v9, 8, v20
	v_lshlrev_b32_e32 v10, 2, v9
	v_add_u32_e32 v131, s9, v10
	v_add_u32_e32 v132, s10, v10
	v_or_b32_e32 v10, 9, v20
	v_lshlrev_b32_e32 v11, 2, v10
	v_add_u32_e32 v133, s9, v11
	v_add_u32_e32 v134, s10, v11
	v_or_b32_e32 v11, 10, v20
	v_lshlrev_b32_e32 v12, 2, v11
	v_add_u32_e32 v135, s9, v12
	v_add_u32_e32 v136, s10, v12
	v_or_b32_e32 v12, 11, v20
	v_lshlrev_b32_e32 v13, 2, v12
	v_add_u32_e32 v137, s9, v13
	v_add_u32_e32 v138, s10, v13
	v_or_b32_e32 v13, 16, v20
	v_lshlrev_b32_e32 v14, 2, v13
	v_add_u32_e32 v139, s9, v14
	v_add_u32_e32 v140, s10, v14
	v_or_b32_e32 v14, 17, v20
	v_lshlrev_b32_e32 v15, 2, v14
	v_add_u32_e32 v141, s9, v15
	v_add_u32_e32 v142, s10, v15
	v_or_b32_e32 v15, 18, v20
	v_lshlrev_b32_e32 v16, 2, v15
	v_add_u32_e32 v143, s9, v16
	v_add_u32_e32 v144, s10, v16
	v_or_b32_e32 v16, 19, v20
	v_lshlrev_b32_e32 v17, 2, v16
	v_add_u32_e32 v145, s9, v17
	v_add_u32_e32 v146, s10, v17
	v_or_b32_e32 v17, 24, v20
	v_lshlrev_b32_e32 v18, 2, v17
	v_add_u32_e32 v147, s9, v18
	v_add_u32_e32 v148, s10, v18
	v_or_b32_e32 v18, 25, v20
	v_lshlrev_b32_e32 v19, 2, v18
	v_writelane_b32 v247, s12, 55
	v_add_u32_e32 v149, s9, v19
	v_add_u32_e32 v150, s10, v19
	v_or_b32_e32 v19, 26, v20
	v_mul_lo_u32 v8, v20, s11
	v_cmp_gt_i32_e64 s[66:67], v1, v20
	v_lshl_or_b32 v70, v20, 6, v1
	v_writelane_b32 v247, s13, 56
	v_cmp_lt_i32_e64 s[12:13], v1, v9
	v_lshlrev_b32_e32 v24, 2, v19
	v_or_b32_e32 v20, 27, v20
	v_lshl_add_u32 v155, v22, 2, v21
	v_lshlrev_b32_e32 v22, 11, v2
	v_lshlrev_b32_e32 v3, 2, v39
	s_movk_i32 s2, 0x118
	v_lshlrev_b32_e32 v64, 6, v23
	v_writelane_b32 v247, s12, 57
	v_add_u32_e32 v151, s9, v24
	v_add_u32_e32 v152, s10, v24
	v_lshlrev_b32_e32 v24, 2, v20
	v_lshl_add_u32 v156, v23, 2, v21
	v_ashrrev_i32_e32 v23, 31, v22
	v_add_u32_e32 v104, s9, v3
	v_lshl_add_u32 v110, v1, 2, s9
	v_writelane_b32 v247, s13, 58
	v_add_u32_e32 v153, s9, v24
	s_movk_i32 s9, 0xf8
	v_mad_u32_u24 v7, v39, s2, v7
	s_movk_i32 s2, 0x1100
	v_lshlrev_b64 v[22:23], 1, v[22:23]
	v_writelane_b32 v247, s9, 59
	s_add_u32 s9, s6, 0xf223840
	v_add3_u32 v157, v7, v5, s8
	v_mul_lo_u32 v7, v2, s2
	v_or_b32_e32 v22, v22, v3
	v_cmp_gt_u32_e32 vcc, 48, v39
	v_add_u32_e32 v105, s10, v3
	v_lshlrev_b32_e32 v107, 4, v2
	v_writelane_b32 v247, s9, 60
	s_addc_u32 s9, s7, 0
	v_or_b32_e32 v158, v7, v3
	v_lshl_or_b32 v160, v2, 13, v5
	v_lshl_add_u64 v[2:3], s[6:7], 0, v[22:23]
	s_mov_b64 s[6:7], 0x6090200
	v_writelane_b32 v247, s9, 61
	v_lshl_add_u64 v[102:103], v[2:3], 0, s[6:7]
	s_xor_b64 s[6:7], vcc, -1
	v_writelane_b32 v247, s6, 62
	s_add_i32 s2, 16, 0x10efc
	v_sub_u32_e32 v2, v4, v5
	v_writelane_b32 v247, s7, 63
	v_writelane_b32 v246, s2, 0
	v_cmp_gt_i32_e64 s[6:7], v1, v9
	v_lshl_or_b32 v78, v9, 6, v1
	v_lshl_or_b32 v80, v10, 6, v1
	v_writelane_b32 v246, s6, 1
	v_lshl_or_b32 v82, v11, 6, v1
	s_waitcnt vmcnt(2)
; __device__ __forceinline__ u16 f2bf(float f) { return (u16)(cvtpk(f, 0.f) & 0xffffu); }
; template <bool SIGNAL>
; __device__ __forceinline__ void phase2(const Params& p, unsigned char* smem, const int lo, const int hi, const int worker, const int nworkers) {
;     ...
;       const int j = 32 * tj + l31; const float gcj = sgc[j];
; #pragma unroll
;       for (int r = 0; r < 16; ++r) {
;         const int i = 32 * ti + 8 * (r >> 2) + 4 * hf + (r & 3);
;         const float gci = sgc[i]; const float bi = sbeta[i];
;         const float dec = __expf(gci - gcj);
;         sM[i * 68 + j] = (j < i) ? bi * kk[r] * dec : 0.f;
;         Ag[i * 64 + j] = f2bf((j <= i) ? qk[r] * dec : 0.f);
;       }
;     }
	v_lshl_or_b32 v84, v12, 6, v1
	v_writelane_b32 v246, s7, 2
	v_cmp_lt_i32_e64 s[6:7], v1, v10
	v_lshl_or_b32 v86, v13, 6, v1
	s_waitcnt vmcnt(1)
	v_lshl_or_b32 v88, v14, 6, v1
	v_writelane_b32 v246, s6, 3
	v_lshl_or_b32 v90, v15, 6, v1
	s_waitcnt vmcnt(0)
	v_lshl_or_b32 v92, v16, 6, v1
	v_writelane_b32 v246, s7, 4
	v_cmp_gt_i32_e64 s[6:7], v1, v10
	v_lshl_or_b32 v94, v17, 6, v1
	v_lshl_or_b32 v96, v18, 6, v1
	v_writelane_b32 v246, s6, 5
	v_lshl_or_b32 v98, v19, 6, v1
	v_lshl_or_b32 v100, v20, 6, v1
	v_writelane_b32 v246, s7, 6
	v_cmp_lt_i32_e64 s[6:7], v1, v11
	v_add_u32_e32 v2, 16, v2
	v_cmp_gt_u32_e64 s[4:5], 64, v32
	v_writelane_b32 v246, s6, 7
	v_mov_b32_e32 v33, v35
	v_lshlrev_b32_e32 v106, 1, v39
	v_writelane_b32 v246, s7, 8
	v_cmp_gt_i32_e64 s[6:7], v1, v11
	v_ashrrev_i32_e32 v41, 31, v32
	v_mov_b32_e32 v40, v32
	v_writelane_b32 v246, s6, 9
	v_add_u32_e32 v44, 0xfffffe80, v42
	v_mov_b32_e32 v45, v35
	v_writelane_b32 v246, s7, 10
	v_cmp_lt_i32_e64 s[6:7], v1, v12
	v_ashrrev_i32_e32 v43, 31, v42
	v_add_u32_e32 v48, 0xfffffe80, v46
	v_writelane_b32 v246, s6, 11
	v_mov_b32_e32 v49, v35
	v_ashrrev_i32_e32 v47, 31, v46
	v_writelane_b32 v246, s7, 12
	v_cmp_gt_i32_e64 s[6:7], v1, v12
	v_add_u32_e32 v52, 0xfffffe80, v50
	v_mov_b32_e32 v53, v35
	v_writelane_b32 v246, s6, 13
	v_ashrrev_i32_e32 v51, 31, v50
	v_add_u32_e32 v56, 0xfffffe80, v54
	v_writelane_b32 v246, s7, 14
	v_cmp_lt_i32_e64 s[6:7], v1, v13
	v_mov_b32_e32 v57, v35
	v_ashrrev_i32_e32 v55, 31, v54
	v_writelane_b32 v246, s6, 15
	v_add_u32_e32 v60, 0xfffffe80, v58
	v_mov_b32_e32 v61, v35
	v_writelane_b32 v246, s7, 16
	v_cmp_gt_i32_e64 s[6:7], v1, v13
	v_ashrrev_i32_e32 v59, 31, v58
	v_cmp_gt_i32_e64 s[62:63], 48, v32
	v_writelane_b32 v246, s6, 17
	v_ashrrev_i32_e32 v63, 31, v62
	v_ashrrev_i32_e32 v65, 31, v64
	v_writelane_b32 v246, s7, 18
	v_cmp_lt_i32_e64 s[6:7], v1, v14
	v_ashrrev_i32_e32 v67, 31, v66
	v_ashrrev_i32_e32 v69, 31, v68
	v_writelane_b32 v246, s6, 19
	v_ashrrev_i32_e32 v71, 31, v70
	v_ashrrev_i32_e32 v73, 31, v72
	v_writelane_b32 v246, s7, 20
	v_cmp_gt_i32_e64 s[6:7], v1, v14
	v_ashrrev_i32_e32 v75, 31, v74
	v_ashrrev_i32_e32 v77, 31, v76
	v_writelane_b32 v246, s6, 21
	v_ashrrev_i32_e32 v79, 31, v78
	v_ashrrev_i32_e32 v81, 31, v80
	v_ashrrev_i32_e32 v83, 31, v82
	v_ashrrev_i32_e32 v85, 31, v84
	v_ashrrev_i32_e32 v87, 31, v86
	v_ashrrev_i32_e32 v89, 31, v88
	v_ashrrev_i32_e32 v91, 31, v90
	v_ashrrev_i32_e32 v93, 31, v92
	v_ashrrev_i32_e32 v95, 31, v94
	v_ashrrev_i32_e32 v97, 31, v96
	v_ashrrev_i32_e32 v99, 31, v98
	v_add_u32_e32 v154, s10, v24
	v_ashrrev_i32_e32 v101, 31, v100
	v_and_b32_e32 v159, 0xffffffc0, v32
	v_add_u32_e32 v161, 0x8600, v2
	v_lshlrev_b32_e32 v34, 1, v0
	s_add_i32 s87, 16, 0xca00
	s_mov_b32 s88, 0x800000
	v_add_u32_e32 v162, v6, v8
	v_mbcnt_hi_u32_b32 v163, -1, v219
	v_mov_b32_e32 v164, 0x300
	v_mov_b32_e32 v165, 0x3db504f3
	s_mov_b32 s2, s89
	v_writelane_b32 v246, s7, 22
	v_cmp_lt_i32_e64 s[10:11], v1, v15
	v_cmp_gt_i32_e64 s[12:13], v1, v15
	v_cmp_lt_i32_e64 s[14:15], v1, v16
	v_cmp_gt_i32_e64 s[16:17], v1, v16
	v_cmp_lt_i32_e64 s[18:19], v1, v17
	v_cmp_gt_i32_e64 s[20:21], v1, v17
	v_cmp_lt_i32_e64 s[6:7], v1, v18
	v_cmp_gt_i32_e64 s[8:9], v1, v18
	v_cmp_lt_i32_e64 s[22:23], v1, v19
	v_cmp_gt_i32_e64 s[24:25], v1, v19
	v_cmp_lt_i32_e64 s[28:29], v1, v20
	v_cmp_gt_i32_e64 s[30:31], v1, v20
	s_mov_b32 s64, 0x358637bd
	s_branch .LBB0_254

; __device__ __forceinline__ void grid_barrier(unsigned* ctr, const unsigned k) {
;   __syncthreads();
;   if (threadIdx.x == 0) {
;     __hip_atomic_fetch_add(ctr, 1u, __ATOMIC_RELEASE, __HIP_MEMORY_SCOPE_AGENT);
;     const unsigned target = k * gridDim.x;
;     while (__hip_atomic_load(ctr, __ATOMIC_RELAXED, __HIP_MEMORY_SCOPE_AGENT) < target) __builtin_amdgcn_s_sleep(1);
;     __builtin_amdgcn_fence(__ATOMIC_ACQUIRE, "agent");
;   }
;   __syncthreads();
; }
.LBB0_346:
	s_barrier
	s_mov_b64 s[4:5], exec
	v_readlane_b32 s6, v247, 0
	v_readlane_b32 s7, v247, 1
	s_and_b64 s[6:7], s[4:5], s[6:7]
	s_mov_b64 exec, s[6:7]
	s_cbranch_execz .LBB0_352
	buffer_wbl2 sc1
	s_waitcnt vmcnt(0)
	v_mov_b32_e32 v0, 0
	v_mov_b32_e32 v1, 1
	global_atomic_add v1, v0, v1, s[44:45] sc0
	s_lshl_b32 s2, s3, 1
	s_waitcnt vmcnt(0)
	v_readfirstlane_b32 s6, v1
	s_nop 3
	s_add_i32 s6, s6, 1
	s_cmp_eq_u32 s6, s2
	s_cbranch_scc0 .Lgbar3_poll
	v_mov_b32_e32 v1, 1
	global_atomic_add v0, v1, s[44:45] offset:1280
	global_atomic_add v0, v1, s[44:45] offset:1344
	global_atomic_add v0, v1, s[44:45] offset:1408
	global_atomic_add v0, v1, s[44:45] offset:1472
	global_atomic_add v0, v1, s[44:45] offset:1536
	global_atomic_add v0, v1, s[44:45] offset:1600
	global_atomic_add v0, v1, s[44:45] offset:1664
	global_atomic_add v0, v1, s[44:45] offset:1728
	s_branch .Lgbar3_done

; __device__ __forceinline__ void grid_barrier(unsigned* ctr, const unsigned k) {
;   __syncthreads();
;   if (threadIdx.x == 0) {
;     __hip_atomic_fetch_add(ctr, 1u, __ATOMIC_RELEASE, __HIP_MEMORY_SCOPE_AGENT);
;     const unsigned target = k * gridDim.x;
;     while (__hip_atomic_load(ctr, __ATOMIC_RELAXED, __HIP_MEMORY_SCOPE_AGENT) < target) __builtin_amdgcn_s_sleep(1);
;     __builtin_amdgcn_fence(__ATOMIC_ACQUIRE, "agent");
;   }
;   __syncthreads();
; }
; __device__ __forceinline__ void phase4(const Params& p, unsigned char* smem) {
;   const u16* hn = (const u16*)p.out; const u16* wtin = hn + (size_t)NTOK * DM;
;   u16* AQ = (u16*)(p.ws + OFF_AQ); u16* DX = (u16*)(p.ws + OFF_DX);
;   u16* SGA = (u16*)(p.ws + OFF_AK); u16* SGD = (u16*)(p.ws + OFF_AVT);
;   const int xcd = blockIdx.x & 7, lw = blockIdx.x >> 3, LW = (gridDim.x - xcd + 7) >> 3;
;   for (int i = lw;; i += LW) {
;     int mt, nt; if (!tile_map(i, xcd, 128, 32, mt, nt)) break;
;     const int m0 = mt * 128;
;     const int n0 = nt < 8 ? 3072 + nt * 128 : (nt < 16 ? 7168 + (nt - 8) * 128 : 8208 + (nt - 16) * 128);
;     f32x16 acc[2][2]; zero_acc(acc);
;     gemm_kloop(acc, [&](int m) { return hn + (size_t)tokrow_of(m) * DM; }, [](int k0) { return (size_t)k0; }, wtin, m0, n0, smem);
.Lgbar3_loop:
	global_load_dword v1, v0, s[44:45] offset:1280 sc1
	s_waitcnt vmcnt(0)
	v_cmp_le_u32_e32 vcc, 3, v1
	s_cbranch_vccnz .Lgbar3_done
	s_sleep 2
	s_branch .Lgbar3_loop
.Lgbar3_done:
	buffer_inv sc1
	s_waitcnt vmcnt(0)
.LBB0_352:
	s_or_b64 exec, exec, s[4:5]
	s_add_u32 s40, s48, 0x2010000
	s_load_dwordx2 s[38:39], s[0:1], 0x60
	s_addc_u32 s41, s49, 0
	s_add_u32 s42, s50, 0x6090000
	s_addc_u32 s43, s51, 0
	s_add_u32 s46, s48, 0x80
	s_addc_u32 s47, s49, 0
	v_mov_b32_e32 v97, 0
	s_mov_b32 s2, 0x10000
	s_mov_b32 s52, 0x20000
	s_mov_b32 s53, 0x30000
	s_movk_i32 s54, 0x90
	s_mov_b32 s55, 0xfffffc0
	s_movk_i32 s56, 0x210
	s_movk_i32 s57, 0x2410
	v_mov_b32_e32 v99, -1
	s_movk_i32 s58, 0x81
	s_mov_b32 s59, 0xc000
	v_mov_b32_e32 v110, 0x358637bd
	s_mov_b32 s60, 0x800000
	s_movk_i32 s61, 0xf000
	v_mov_b32_e32 v111, 0xffffb7e0
	v_mov_b32_e32 v112, 0xffffbfe0
	v_mov_b32_e32 v113, 0x4050000
	v_mov_b32_e32 v114, 0x2010000
	s_mov_b32 s62, s33
	s_waitcnt lgkmcnt(0)
	s_barrier
	s_branch .LBB0_355

; __device__ __forceinline__ void grid_barrier(unsigned* ctr, const unsigned k) {
;   __syncthreads();
;   if (threadIdx.x == 0) {
;     __hip_atomic_fetch_add(ctr, 1u, __ATOMIC_RELEASE, __HIP_MEMORY_SCOPE_AGENT);
;     const unsigned target = k * gridDim.x;
;     while (__hip_atomic_load(ctr, __ATOMIC_RELAXED, __HIP_MEMORY_SCOPE_AGENT) < target) __builtin_amdgcn_s_sleep(1);
;     __builtin_amdgcn_fence(__ATOMIC_ACQUIRE, "agent");
;   }
;   __syncthreads();
; }
.LBB0_387:
	v_readlane_b32 s42, v247, 0
	v_readlane_b32 s43, v247, 1
	s_barrier
	s_and_saveexec_b64 s[4:5], s[42:43]
	s_cbranch_execz .LBB0_393
	buffer_wbl2 sc1
	s_waitcnt vmcnt(0)
	v_mov_b32_e32 v0, 0
	v_mov_b32_e32 v1, 1
	global_atomic_add v1, v0, v1, s[44:45] sc0
	s_mul_i32 s2, s3, 3
	s_waitcnt vmcnt(0)
	v_readfirstlane_b32 s6, v1
	s_nop 3
	s_add_i32 s6, s6, 1
	s_cmp_eq_u32 s6, s2
	s_cbranch_scc0 .Lgbar4_poll
	v_mov_b32_e32 v1, 1
	global_atomic_add v0, v1, s[44:45] offset:1280
	global_atomic_add v0, v1, s[44:45] offset:1344
	global_atomic_add v0, v1, s[44:45] offset:1408
	global_atomic_add v0, v1, s[44:45] offset:1472
	global_atomic_add v0, v1, s[44:45] offset:1536
	global_atomic_add v0, v1, s[44:45] offset:1600
	global_atomic_add v0, v1, s[44:45] offset:1664
	global_atomic_add v0, v1, s[44:45] offset:1728
	s_branch .Lgbar4_done

; __device__ __forceinline__ void grid_barrier(unsigned* ctr, const unsigned k) {
;   __syncthreads();
;   if (threadIdx.x == 0) {
;     __hip_atomic_fetch_add(ctr, 1u, __ATOMIC_RELEASE, __HIP_MEMORY_SCOPE_AGENT);
;     const unsigned target = k * gridDim.x;
;     while (__hip_atomic_load(ctr, __ATOMIC_RELAXED, __HIP_MEMORY_SCOPE_AGENT) < target) __builtin_amdgcn_s_sleep(1);
;     __builtin_amdgcn_fence(__ATOMIC_ACQUIRE, "agent");
;   }
;   __syncthreads();
; }
; __device__ __forceinline__ void phase5(const Params& p, unsigned char* smem) {
;   const u16* AQ = (const u16*)(p.ws + OFF_AQ); const u16* DX = (const u16*)(p.ws + OFF_DX);
;   const u16* SGA = (const u16*)(p.ws + OFF_AK); const u16* SGD = (const u16*)(p.ws + OFF_AVT);
;   const u16* wat = (const u16*)(p.ws + OFF_W3); const u16* wdt = wat + 1024 * 1024;
;   u16* MERGED = (u16*)(p.ws + OFF_EXTRA);
;   const int xcd = blockIdx.x & 7, lw = blockIdx.x >> 3, LW = (gridDim.x - xcd + 7) >> 3;
;   for (int i = lw;; i += LW) {
;     int mt, nt; if (!tile_map(i, xcd, 128, 8, mt, nt)) break;
;     const int m0 = mt * 128, n0 = nt * 128;
;     f32x16 acc[2][2]; zero_acc(acc);
;     gemm_kloop(acc, [&](int m) { return AQ + (size_t)tokrow_of(m) * 1024; }, [](int k0) { return (size_t)k0; }, wat, m0, n0, smem);
.Lgbar4_loop:
	global_load_dword v1, v0, s[44:45] offset:1280 sc1
	s_waitcnt vmcnt(0)
	v_cmp_le_u32_e32 vcc, 4, v1
	s_cbranch_vccnz .Lgbar4_done
	s_sleep 2
	s_branch .Lgbar4_loop
.Lgbar4_done:
	buffer_inv sc1
	s_waitcnt vmcnt(0)
.LBB0_393:
	s_or_b64 exec, exec, s[4:5]
	s_cmpk_lt_u32 s89, 0x400
	s_cselect_b64 s[4:5], -1, 0
	s_cmpk_gt_u32 s89, 0x3ff
	s_barrier
	s_cbranch_scc1 .LBB0_418
	s_add_u32 s8, s36, 0x2010000
	s_addc_u32 s9, s37, 0
	s_add_u32 s10, s36, 0xe81d000
	s_addc_u32 s11, s37, 0
	s_add_u32 s6, s36, 0xc5d9000
	s_addc_u32 s7, s37, 0
	s_lshr_b32 s2, s89, 6
	s_and_b32 s18, s2, 8
	s_lshl_b32 s2, s73, 7
	s_add_u32 s12, s36, 0x80
	s_addc_u32 s13, s37, 0
	v_mov_b32_e32 v97, 0
	s_mov_b32 s19, 0x10000
	s_mov_b32 s20, 0x20000
	s_mov_b32 s21, 0x30000
	s_movk_i32 s22, 0x90
	s_mov_b32 s23, 0xfffffc0
	s_movk_i32 s24, 0x210
	s_mov_b32 s16, s18
	s_mov_b32 s25, s33
	s_branch .LBB0_396

; __device__ __forceinline__ void grid_barrier(unsigned* ctr, const unsigned k) {
;   __syncthreads();
;   if (threadIdx.x == 0) {
;     __hip_atomic_fetch_add(ctr, 1u, __ATOMIC_RELEASE, __HIP_MEMORY_SCOPE_AGENT);
;     const unsigned target = k * gridDim.x;
;     while (__hip_atomic_load(ctr, __ATOMIC_RELAXED, __HIP_MEMORY_SCOPE_AGENT) < target) __builtin_amdgcn_s_sleep(1);
;     __builtin_amdgcn_fence(__ATOMIC_ACQUIRE, "agent");
;   }
;   __syncthreads();
; }
.LBB0_418:
	s_barrier
	s_and_saveexec_b64 s[6:7], s[42:43]
	s_cbranch_execz .LBB0_424
	buffer_wbl2 sc1
	s_waitcnt vmcnt(0)
	v_mov_b32_e32 v0, 0
	v_mov_b32_e32 v1, 1
	global_atomic_add v1, v0, v1, s[44:45] sc0
	s_lshl_b32 s2, s3, 2
	s_waitcnt vmcnt(0)
	v_readfirstlane_b32 s8, v1
	s_nop 3
	s_add_i32 s8, s8, 1
	s_cmp_eq_u32 s8, s2
	s_cbranch_scc0 .Lgbar5_poll
	v_mov_b32_e32 v1, 1
	global_atomic_add v0, v1, s[44:45] offset:1280
	global_atomic_add v0, v1, s[44:45] offset:1344
	global_atomic_add v0, v1, s[44:45] offset:1408
	global_atomic_add v0, v1, s[44:45] offset:1472
	global_atomic_add v0, v1, s[44:45] offset:1536
	global_atomic_add v0, v1, s[44:45] offset:1600
	global_atomic_add v0, v1, s[44:45] offset:1664
	global_atomic_add v0, v1, s[44:45] offset:1728
	s_branch .Lgbar5_done

; __device__ __forceinline__ void grid_barrier(unsigned* ctr, const unsigned k) {
;   __syncthreads();
;   if (threadIdx.x == 0) {
;     __hip_atomic_fetch_add(ctr, 1u, __ATOMIC_RELEASE, __HIP_MEMORY_SCOPE_AGENT);
;     const unsigned target = k * gridDim.x;
;     while (__hip_atomic_load(ctr, __ATOMIC_RELAXED, __HIP_MEMORY_SCOPE_AGENT) < target) __builtin_amdgcn_s_sleep(1);
;     __builtin_amdgcn_fence(__ATOMIC_ACQUIRE, "agent");
;   }
;   __syncthreads();
; }
; __device__ __forceinline__ void phase6(const Params& p, unsigned char* smem) {
;   const u16* MERGED = (const u16*)(p.ws + OFF_EXTRA);
;   const u16* wot = (const u16*)(p.ws + OFF_W3) + 2 * 1024 * 1024;
;   float* PSUM = (float*)(p.ws + OFF_PSUM);
;   const int xcd = blockIdx.x & 7, lw = blockIdx.x >> 3, LW = (gridDim.x - xcd + 7) >> 3;
;   for (int i = lw;; i += LW) {
;     int mt, nt; if (!tile_map(i, xcd, 128, 8, mt, nt)) break;
;     const int m0 = mt * 128, n0 = nt * 128;
;     f32x16 acc[2][2]; zero_acc(acc);
;     gemm_kloop(acc, [&](int m) { return MERGED + (size_t)m * 1024; }, [](int k0) { return (size_t)k0; }, wot, m0, n0, smem);
.Lgbar5_loop:
	global_load_dword v1, v0, s[44:45] offset:1280 sc1
	s_waitcnt vmcnt(0)
	v_cmp_le_u32_e32 vcc, 5, v1
	s_cbranch_vccnz .Lgbar5_done
	s_sleep 2
	s_branch .Lgbar5_loop
.Lgbar5_done:
	buffer_inv sc1
	s_waitcnt vmcnt(0)
.LBB0_424:
	s_or_b64 exec, exec, s[6:7]
	s_andn2_b64 vcc, exec, s[4:5]
	s_barrier
	s_cbranch_vccnz .LBB0_441
	s_add_u32 s4, s36, 0xc5d9000
	s_addc_u32 s5, s37, 0
	s_add_u32 s6, s36, 0xec1d000
	s_addc_u32 s7, s37, 0
	s_add_u32 s2, s36, 0xf123000
	s_addc_u32 s26, s37, 0
	s_lshr_b32 s8, s89, 6
	s_and_b32 s22, s8, 8
	s_load_dwordx2 s[8:9], s[0:1], 0x0
	s_load_dwordx2 s[10:11], s[0:1], 0x88
	s_lshl_b32 s27, s73, 7
	s_add_u32 s12, s36, 0xc5d9080
	s_addc_u32 s13, s37, 0
	v_mov_b32_e32 v97, 0
	s_mov_b64 s[14:15], 0x10000
	s_mov_b64 s[16:17], 0x20000
	s_mov_b64 s[18:19], 0x30000
	s_mov_b32 s28, 0x10000
	s_mov_b32 s29, 0x20000
	s_mov_b32 s30, 0x30000
	s_movk_i32 s31, 0x90
	s_mov_b32 s34, 0xfffffc0
	s_movk_i32 s35, 0x210
	s_branch .LBB0_428

; __device__ __forceinline__ void grid_barrier(unsigned* ctr, const unsigned k) {
;   __syncthreads();
;   if (threadIdx.x == 0) {
;     __hip_atomic_fetch_add(ctr, 1u, __ATOMIC_RELEASE, __HIP_MEMORY_SCOPE_AGENT);
;     const unsigned target = k * gridDim.x;
;     while (__hip_atomic_load(ctr, __ATOMIC_RELAXED, __HIP_MEMORY_SCOPE_AGENT) < target) __builtin_amdgcn_s_sleep(1);
;     __builtin_amdgcn_fence(__ATOMIC_ACQUIRE, "agent");
;   }
;   __syncthreads();
; }
.LBB0_441:
	s_waitcnt lgkmcnt(0)
	s_barrier
	s_and_saveexec_b64 s[4:5], s[42:43]
	s_cbranch_execz .LBB0_447
	buffer_wbl2 sc1
	s_waitcnt vmcnt(0)
	v_mov_b32_e32 v0, 0
	v_mov_b32_e32 v1, 1
	global_atomic_add v1, v0, v1, s[44:45] sc0
	s_mul_i32 s2, s3, 5
	s_waitcnt vmcnt(0)
	v_readfirstlane_b32 s6, v1
	s_nop 3
	s_add_i32 s6, s6, 1
	s_cmp_eq_u32 s6, s2
	s_cbranch_scc0 .Lgbar6_poll
	v_mov_b32_e32 v1, 1
	global_atomic_add v0, v1, s[44:45] offset:1280
	global_atomic_add v0, v1, s[44:45] offset:1344
	global_atomic_add v0, v1, s[44:45] offset:1408
	global_atomic_add v0, v1, s[44:45] offset:1472
	global_atomic_add v0, v1, s[44:45] offset:1536
	global_atomic_add v0, v1, s[44:45] offset:1600
	global_atomic_add v0, v1, s[44:45] offset:1664
	global_atomic_add v0, v1, s[44:45] offset:1728
	s_branch .Lgbar6_done

; __device__ __forceinline__ int ltid() { int t = threadIdx.x; asm volatile("" : "+v"(t)); return t; }
; __device__ __forceinline__ void grid_barrier(unsigned* ctr, const unsigned k) {
;   __syncthreads();
;   if (threadIdx.x == 0) {
;     __hip_atomic_fetch_add(ctr, 1u, __ATOMIC_RELEASE, __HIP_MEMORY_SCOPE_AGENT);
;     const unsigned target = k * gridDim.x;
;     while (__hip_atomic_load(ctr, __ATOMIC_RELAXED, __HIP_MEMORY_SCOPE_AGENT) < target) __builtin_amdgcn_s_sleep(1);
;     __builtin_amdgcn_fence(__ATOMIC_ACQUIRE, "agent");
;   }
;   __syncthreads();
; }
; __device__ __forceinline__ void phase7(const Params& p) {
;   const float* PSUM = (const float*)(p.ws + OFF_PSUM);
;   const int tid__ = ltid(); const int lane = tid__ & 63, wave = tid__ >> 6;
;   for (int it = blockIdx.x; it < NX / 4; it += gridDim.x) {
;     int row = it * 4 + wave;
;     float tot = 0.f;
; #pragma unroll
;     for (int j = 0; j < 8; ++j) tot += PSUM[(size_t)j * NX + row];
;     float rs = rsqrtf(tot * (1.f / 1024.f) + 1e-6f);
;     float4* o = (float4*)(p.out + (size_t)row * 1024);
.Lgbar6_loop:
	global_load_dword v1, v0, s[44:45] offset:1280 sc1
	s_waitcnt vmcnt(0)
	v_cmp_le_u32_e32 vcc, 6, v1
	s_cbranch_vccnz .Lgbar6_done
	s_sleep 2
	s_branch .Lgbar6_loop
.Lgbar6_done:
	buffer_inv sc1
	s_waitcnt vmcnt(0)
.LBB0_447:
	s_or_b64 exec, exec, s[4:5]
	s_cmpk_gt_i32 s89, 0xfff
	s_barrier
	s_cbranch_scc1 .LBB0_450
	s_load_dwordx4 s[4:7], s[0:1], 0x80
	v_and_b32_e32 v0, 63, v218
	s_add_u32 s0, s36, 0xf123000
	v_ashrrev_i32_e32 v4, 6, v218
	v_lshlrev_b32_e32 v2, 4, v0
	v_mov_b32_e32 v3, 0
	s_addc_u32 s1, s37, 0
	s_waitcnt lgkmcnt(0)
	v_lshl_add_u64 v[0:1], s[4:5], 0, v[2:3]
	v_lshl_add_u64 v[2:3], s[6:7], 0, v[2:3]
	v_lshl_add_u32 v4, s89, 2, v4
	s_lshl_b32 s2, s3, 2
	v_mov_b32_e32 v6, 0x358637bd
	s_mov_b32 s4, 0x800000
